# v28 + weight-prep gain loads issued ahead of the weight loads + attention combine: other-branch outputs loaded early in the round (no exposed wait), obsolete counted waits removed
# baseline (speedup 1.0000x reference)
; #define LAS __attribute__((address_space(3)))
; __device__ __forceinline__ void transpose_item(const float* W, int K, int N, bf16_t* WT, int k0, int src_n0, int dst_n0, LAS float* scr, int lane, const float* st, float* sw, const float* gt, size_t cstride) {
;     { f32x4 v[8]; const int c4 = lane & 7, kr = lane >> 3;
; #pragma unroll
;         for (int i = 0; i < 8; ++i) v[i] = __builtin_nontemporal_load((const f32x4*)(W + (size_t)(k0 + 8 * i + kr) * N + src_n0 + 4 * c4));
; #pragma unroll
;         for (int i = 0; i < 8; ++i) { LAS float* d = scr + (8 * i + kr) * 33 + 4 * c4; d[0] = v[i].x; d[1] = v[i].y; d[2] = v[i].z; d[3] = v[i].w; } }
;     asm volatile("s_waitcnt lgkmcnt(0)" ::: "memory");
;     const int c = lane & 7;
;     if (!gt) {
; #pragma unroll
;         for (int j = 0; j < 4; ++j) { const int n = (lane >> 3) + 8 * j; const LAS float* s = scr + (8 * c) * 33 + n;
;             u32x4 o; o.x = cvt_pk_bf16(s[0 * 33], s[1 * 33]); o.y = cvt_pk_bf16(s[2 * 33], s[3 * 33]); o.z = cvt_pk_bf16(s[4 * 33], s[5 * 33]); o.w = cvt_pk_bf16(s[6 * 33], s[7 * 33]);
;             __builtin_nontemporal_store(o, (u32x4*)(WT + (size_t)(dst_n0 + n) * K + k0 + 8 * c)); }
;     } else {
;         f32x4 gk[8];
; #pragma unroll
;         for (int i = 0; i < 8; ++i) gk[i] = *(const f32x4*)(gt + (size_t)(k0 + 8 * c + i) * NB);
.LBB0_33:
	s_mov_b64 s[48:49], s[80:81]
	s_lshl_b32 s28, s7, 5
	s_mul_i32 s5, s22, 0xc00000
	s_mov_b64 s[50:51], s[82:83]
	s_mul_hi_i32 s4, s22, 0xc00000
	s_add_u32 s7, s50, s5
	s_addc_u32 s40, s51, s4
	s_lshl_b32 s4, s6, 6
	s_mul_i32 s6, s22, 3
	s_and_b32 s29, s4, 0xffc0
	s_add_i32 s4, s6, 1
	s_ashr_i32 s5, s4, 31
	s_lshl_b64 s[24:25], s[4:5], 14
	s_add_u32 s24, s11, s24
	s_addc_u32 s25, s14, s25
	s_lshl_b64 s[38:39], s[12:13], 2
	s_add_u32 s38, s7, s38
	s_addc_u32 s39, s40, s39
	v_add_u32_e32 v30, s29, v37
	v_lshl_add_u64 v[28:29], s[38:39], 0, v[168:169]
	s_movk_i32 s5, 0x3000
	v_mad_i64_i32 v[0:1], s[38:39], v30, s5, v[28:29]
	v_or_b32_e32 v218, s29, v36
	v_lshlrev_b32_e32 v218, 4, v218
	global_load_dwordx4 v[186:189], v218, s[24:25] offset:32
	global_load_dwordx4 v[190:193], v218, s[24:25] offset:48
	global_load_dwordx4 v[194:197], v218, s[24:25]
	global_load_dwordx4 v[198:201], v218, s[24:25] offset:16
	global_load_dwordx4 v[202:205], v218, s[24:25] offset:96
	global_load_dwordx4 v[206:209], v218, s[24:25] offset:112
	global_load_dwordx4 v[210:213], v218, s[24:25] offset:64
	global_load_dwordx4 v[214:217], v218, s[24:25] offset:80
	global_load_dwordx4 v[0:3], v[0:1], off nt
	s_waitcnt lgkmcnt(3)
	v_add_u32_e32 v4, 8, v30
	s_waitcnt lgkmcnt(2)
	v_mad_i64_i32 v[4:5], s[38:39], v4, s5, v[28:29]
	s_waitcnt lgkmcnt(0)
	global_load_dwordx4 v[4:7], v[4:5], off nt
	v_add_u32_e32 v8, 16, v30
	v_mad_i64_i32 v[8:9], s[38:39], v8, s5, v[28:29]
	global_load_dwordx4 v[8:11], v[8:9], off nt
	v_add_u32_e32 v12, 24, v30
	v_mad_i64_i32 v[12:13], s[38:39], v12, s5, v[28:29]
	global_load_dwordx4 v[12:15], v[12:13], off nt
	v_add_u32_e32 v16, 32, v30
	v_mad_i64_i32 v[16:17], s[38:39], v16, s5, v[28:29]
	global_load_dwordx4 v[16:19], v[16:17], off nt
	v_add_u32_e32 v20, 40, v30
	v_mad_i64_i32 v[20:21], s[38:39], v20, s5, v[28:29]
	global_load_dwordx4 v[20:23], v[20:21], off nt
	v_add_u32_e32 v24, 48, v30
	v_mad_i64_i32 v[24:25], s[38:39], v24, s5, v[28:29]
	global_load_dwordx4 v[24:27], v[24:25], off nt
	v_add_u32_e32 v30, 56, v30
	v_mad_i64_i32 v[28:29], s[38:39], v30, s5, v[28:29]
	global_load_dwordx4 v[28:31], v[28:29], off nt
	s_lshl_b32 s5, s29, 1
	v_mov_b32_e32 v41, v169
	s_mov_b32 s7, 0x600000
	s_mov_b32 s12, 0xc00000
	s_mov_b64 s[52:53], s[84:85]
	s_mov_b64 s[54:55], s[86:87]
	s_waitcnt vmcnt(7)
	ds_write2_b32 v84, v0, v1 offset1:1
	ds_write2_b32 v84, v2, v3 offset0:2 offset1:3
	s_waitcnt vmcnt(6)
	ds_write2_b32 v85, v4, v5 offset1:1
	ds_write2_b32 v86, v6, v7 offset1:1
	s_waitcnt vmcnt(5)
	ds_write2_b32 v87, v8, v9 offset1:1
	ds_write2_b32 v88, v10, v11 offset1:1
	s_waitcnt vmcnt(4)
	ds_write2_b32 v89, v12, v13 offset1:1
	ds_write2_b32 v90, v14, v15 offset1:1
	s_waitcnt vmcnt(3)
	ds_write2_b32 v91, v16, v17 offset1:1
	ds_write2_b32 v92, v18, v19 offset1:1
	s_waitcnt vmcnt(2)
	ds_write2_b32 v93, v20, v21 offset1:1
	ds_write2_b32 v94, v22, v23 offset1:1
	s_waitcnt vmcnt(1)
	ds_write2_b32 v95, v24, v25 offset1:1
	ds_write2_b32 v96, v26, v27 offset1:1
	s_waitcnt vmcnt(0)
	ds_write2_b32 v97, v28, v29 offset1:1
	ds_write2_b32 v98, v30, v31 offset1:1
	v_or_b32_e32 v0, s29, v36
	s_waitcnt lgkmcnt(0)
	v_lshlrev_b32_e32 v12, 4, v0
	v_mov_b32_e32 v16, v186
	v_mov_b32_e32 v17, v187
	v_mov_b32_e32 v18, v188
	v_mov_b32_e32 v19, v189
	v_mov_b32_e32 v0, v190
	v_mov_b32_e32 v1, v191
	v_mov_b32_e32 v2, v192
	v_mov_b32_e32 v3, v193
	v_mov_b32_e32 v24, v194
	v_mov_b32_e32 v25, v195
	v_mov_b32_e32 v26, v196
	v_mov_b32_e32 v27, v197
	v_mov_b32_e32 v8, v198
	v_mov_b32_e32 v9, v199
	v_mov_b32_e32 v10, v200
	v_mov_b32_e32 v11, v201
	v_mov_b32_e32 v20, v202
	v_mov_b32_e32 v21, v203
	v_mov_b32_e32 v22, v204
	v_mov_b32_e32 v23, v205
	v_mov_b32_e32 v4, v206
	v_mov_b32_e32 v5, v207
	v_mov_b32_e32 v6, v208
	v_mov_b32_e32 v7, v209
	v_mov_b32_e32 v28, v210
	v_mov_b32_e32 v29, v211
	v_mov_b32_e32 v30, v212
	v_mov_b32_e32 v31, v213
	s_nop 0
	v_mov_b32_e32 v12, v214
	v_mov_b32_e32 v13, v215
	v_mov_b32_e32 v14, v216
	v_mov_b32_e32 v15, v217
	s_add_u32 s24, s23, s5
	ds_read2_b32 v[58:59], v80 offset0:33 offset1:41
	ds_read2_b32 v[64:65], v80 offset0:66 offset1:74
	ds_read2_b32 v[56:57], v80 offset0:99 offset1:107
	ds_read2_b32 v[62:63], v80 offset0:132 offset1:140
	ds_read2_b32 v[54:55], v80 offset0:165 offset1:173
	ds_read2_b32 v[60:61], v80 offset0:198 offset1:206
	ds_read2_b32 v[52:53], v80 offset0:231 offset1:239
	ds_read2_b32 v[66:67], v80 offset1:8
	s_addc_u32 s25, s26, 0
	v_lshl_add_u64 v[32:33], s[24:25], 0, v[40:41]
	s_mov_b64 s[24:25], 0x5800000
	v_lshl_add_u64 v[42:43], v[32:33], 0, s[24:25]
	v_add_u32_e32 v32, s28, v37
	v_ashrrev_i32_e32 v33, 31, v32
	v_lshlrev_b64 v[32:33], 11, v[32:33]
	s_waitcnt lgkmcnt(0)
	v_mov_b32_e32 v70, v66
	v_mov_b32_e32 v71, v58
	v_mov_b32_e32 v72, v64
	v_mov_b32_e32 v73, v56
	v_lshl_add_u64 v[68:69], v[42:43], 0, v[32:33]
	v_mov_b32_e32 v74, v62
	v_mov_b32_e32 v75, v54
	v_mov_b32_e32 v76, v60
	v_mov_b32_e32 v77, v52
	s_mov_b32 s24, 0x1200000
	v_mov_b32_e32 v58, v67
	v_mov_b32_e32 v56, v65
	v_mov_b32_e32 v54, v63
	v_mov_b32_e32 v52, v61
	s_mov_b32 s5, 0
	s_waitcnt vmcnt(7)
	v_mov_b32_e32 v46, v16
	s_waitcnt vmcnt(6)
	v_mov_b32_e32 v47, v0
	s_waitcnt vmcnt(5)
	v_mov_b32_e32 v44, v24
	s_waitcnt vmcnt(4)
	v_mov_b32_e32 v45, v8
	v_pk_mul_f32 v[32:33], v[44:45], v[70:71]
	v_pk_mul_f32 v[34:35], v[46:47], v[72:73]
	s_waitcnt vmcnt(1)
	v_mov_b32_e32 v48, v28
	s_waitcnt vmcnt(0)
; #define LAS __attribute__((address_space(3)))
; __device__ __forceinline__ void transpose_item(const float* W, int K, int N, bf16_t* WT, int k0, int src_n0, int dst_n0, LAS float* scr, int lane, const float* st, float* sw, const float* gt, size_t cstride) {
;     ...
;         for (int j = 0; j < 4; ++j) { const int n = (lane >> 3) + 8 * j; const LAS float* s = scr + (8 * c) * 33 + n;
;             float w[8];
; #pragma unroll
;             for (int i = 0; i < 8; ++i) w[i] = s[i * 33];
; #pragma unroll
;             for (int b = 0; b < NB; ++b) {
;                 u32x4 o; o.x = cvt_pk_bf16(w[0] * gk[0][b], w[1] * gk[1][b]); o.y = cvt_pk_bf16(w[2] * gk[2][b], w[3] * gk[3][b]); o.z = cvt_pk_bf16(w[4] * gk[4][b], w[5] * gk[5][b]); o.w = cvt_pk_bf16(w[6] * gk[6][b], w[7] * gk[7][b]);
;                 __builtin_nontemporal_store(o, (u32x4*)(WT + (size_t)b * cstride + (size_t)(dst_n0 + n) * K + k0 + 8 * c)); } }
	v_mov_b32_e32 v49, v12
	v_mov_b32_e32 v50, v20
	v_mov_b32_e32 v51, v4
	v_cvt_pk_bf16_f32 v32, v32, v33
	v_cvt_pk_bf16_f32 v33, v34, v35
	v_pk_mul_f32 v[34:35], v[48:49], v[74:75]
	v_pk_mul_f32 v[100:101], v[50:51], v[76:77]
	v_mov_b32_e32 v0, v17
	v_cvt_pk_bf16_f32 v34, v34, v35
	v_cvt_pk_bf16_f32 v35, v100, v101
	v_pk_mul_f32 v[16:17], v[0:1], v[72:73]
	v_mov_b32_e32 v12, v29
	global_store_dwordx4 v[68:69], v[32:35], off nt
	v_mov_b32_e32 v4, v21
	v_mov_b32_e32 v8, v25
	v_cvt_pk_bf16_f32 v33, v16, v17
	v_pk_mul_f32 v[16:17], v[12:13], v[74:75]
	v_pk_mul_f32 v[24:25], v[8:9], v[70:71]
	v_cvt_pk_bf16_f32 v34, v16, v17
	v_pk_mul_f32 v[16:17], v[4:5], v[76:77]
	v_cvt_pk_bf16_f32 v32, v24, v25
	v_cvt_pk_bf16_f32 v35, v16, v17
	v_add_co_u32_e32 v16, vcc, s7, v68
	s_nop 1
	v_addc_co_u32_e32 v17, vcc, 0, v69, vcc
	global_store_dwordx4 v[16:17], v[32:35], off nt
	v_mov_b32_e32 v16, v26
	v_mov_b32_e32 v17, v10
	v_pk_mul_f32 v[20:21], v[16:17], v[70:71]
	v_mov_b32_e32 v10, v27
	v_cvt_pk_bf16_f32 v32, v20, v21
	v_mov_b32_e32 v20, v18
	v_mov_b32_e32 v21, v2
	v_pk_mul_f32 v[24:25], v[20:21], v[72:73]
	v_mov_b32_e32 v2, v19
	v_cvt_pk_bf16_f32 v33, v24, v25
	v_mov_b32_e32 v24, v30
	v_mov_b32_e32 v25, v14
	v_pk_mul_f32 v[28:29], v[24:25], v[74:75]
	v_pk_mul_f32 v[18:19], v[2:3], v[72:73]
	v_cvt_pk_bf16_f32 v34, v28, v29
	v_mov_b32_e32 v28, v22
	v_mov_b32_e32 v29, v6
	v_pk_mul_f32 v[100:101], v[28:29], v[76:77]
	v_mov_b32_e32 v14, v31
	v_cvt_pk_bf16_f32 v35, v100, v101
	v_add_co_u32_e32 v100, vcc, s12, v68
	v_mov_b32_e32 v6, v23
	s_nop 0
	v_addc_co_u32_e32 v101, vcc, 0, v69, vcc
	global_store_dwordx4 v[100:101], v[32:35], off nt
	v_pk_mul_f32 v[26:27], v[10:11], v[70:71]
	v_pk_mul_f32 v[22:23], v[44:45], v[58:59]
	v_cvt_pk_bf16_f32 v33, v18, v19
	v_pk_mul_f32 v[18:19], v[14:15], v[74:75]
	v_cvt_pk_bf16_f32 v32, v26, v27
	v_cvt_pk_bf16_f32 v34, v18, v19
	v_pk_mul_f32 v[18:19], v[6:7], v[76:77]
	v_cvt_pk_bf16_f32 v30, v22, v23
	v_cvt_pk_bf16_f32 v35, v18, v19
	v_add_co_u32_e32 v18, vcc, s24, v68
	v_pk_mul_f32 v[22:23], v[46:47], v[56:57]
	s_nop 0
	v_addc_co_u32_e32 v19, vcc, 0, v69, vcc
	global_store_dwordx4 v[18:19], v[32:35], off nt
	v_add_u32_e32 v18, s28, v39
	v_ashrrev_i32_e32 v19, 31, v18
	v_cvt_pk_bf16_f32 v31, v22, v23
	v_pk_mul_f32 v[22:23], v[48:49], v[54:55]
	v_lshlrev_b64 v[18:19], 11, v[18:19]
	v_cvt_pk_bf16_f32 v32, v22, v23
	v_pk_mul_f32 v[22:23], v[50:51], v[52:53]
	v_lshl_add_u64 v[18:19], v[42:43], 0, v[18:19]
	v_cvt_pk_bf16_f32 v33, v22, v23
	v_pk_mul_f32 v[22:23], v[8:9], v[58:59]
	global_store_dwordx4 v[18:19], v[30:33], off nt
	s_nop 1
	v_cvt_pk_bf16_f32 v30, v22, v23
	v_pk_mul_f32 v[22:23], v[0:1], v[56:57]
	s_nop 0
	v_cvt_pk_bf16_f32 v31, v22, v23
	v_pk_mul_f32 v[22:23], v[12:13], v[54:55]
	s_nop 0
	v_cvt_pk_bf16_f32 v32, v22, v23
	v_pk_mul_f32 v[22:23], v[4:5], v[52:53]
	s_nop 0
	v_cvt_pk_bf16_f32 v33, v22, v23
	v_add_co_u32_e32 v22, vcc, s7, v18
	s_nop 1
	v_addc_co_u32_e32 v23, vcc, 0, v19, vcc
	global_store_dwordx4 v[22:23], v[30:33], off nt
	v_pk_mul_f32 v[22:23], v[16:17], v[58:59]
	s_nop 0
	v_cvt_pk_bf16_f32 v30, v22, v23
	v_pk_mul_f32 v[22:23], v[20:21], v[56:57]
	s_nop 0
	v_cvt_pk_bf16_f32 v31, v22, v23
	v_pk_mul_f32 v[22:23], v[24:25], v[54:55]
	s_nop 0
	v_cvt_pk_bf16_f32 v32, v22, v23
	v_pk_mul_f32 v[22:23], v[28:29], v[52:53]
	s_nop 0
	v_cvt_pk_bf16_f32 v33, v22, v23
	v_add_co_u32_e32 v22, vcc, s12, v18
	s_nop 1
	v_addc_co_u32_e32 v23, vcc, 0, v19, vcc
	global_store_dwordx4 v[22:23], v[30:33], off nt
	v_pk_mul_f32 v[22:23], v[10:11], v[58:59]
	v_add_co_u32_e32 v18, vcc, s24, v18
	v_cvt_pk_bf16_f32 v30, v22, v23
	v_pk_mul_f32 v[22:23], v[2:3], v[56:57]
	v_addc_co_u32_e32 v19, vcc, 0, v19, vcc
	v_cvt_pk_bf16_f32 v31, v22, v23
	v_pk_mul_f32 v[22:23], v[14:15], v[54:55]
	s_nop 0
	v_cvt_pk_bf16_f32 v32, v22, v23
	v_pk_mul_f32 v[22:23], v[6:7], v[52:53]
	s_nop 0
	v_cvt_pk_bf16_f32 v33, v22, v23
	global_store_dwordx4 v[18:19], v[30:33], off nt
	ds_read2_b32 v[18:19], v80 offset0:16 offset1:24
	ds_read2_b32 v[22:23], v80 offset0:49 offset1:57
	ds_read2_b32 v[26:27], v80 offset0:82 offset1:90
	ds_read2_b32 v[34:35], v80 offset0:115 offset1:123
	ds_read2_b32 v[52:53], v80 offset0:148 offset1:156
	ds_read2_b32 v[54:55], v80 offset0:181 offset1:189
	ds_read2_b32 v[56:57], v80 offset0:214 offset1:222
	ds_read2_b32 v[58:59], v80 offset0:247 offset1:255
	v_add_u32_e32 v30, s28, v78
	v_ashrrev_i32_e32 v31, 31, v30
	v_lshlrev_b64 v[30:31], 11, v[30:31]
	s_waitcnt lgkmcnt(7)
; #define LAS __attribute__((address_space(3)))
; __device__ __forceinline__ void transpose_item(const float* W, int K, int N, bf16_t* WT, int k0, int src_n0, int dst_n0, LAS float* scr, int lane, const float* st, float* sw, const float* gt, size_t cstride) {
;     ...
;         for (int j = 0; j < 4; ++j) { const int n = (lane >> 3) + 8 * j; const LAS float* s = scr + (8 * c) * 33 + n;
;             float w[8];
; #pragma unroll
;             for (int i = 0; i < 8; ++i) w[i] = s[i * 33];
; #pragma unroll
;             for (int b = 0; b < NB; ++b) {
;                 u32x4 o; o.x = cvt_pk_bf16(w[0] * gk[0][b], w[1] * gk[1][b]); o.y = cvt_pk_bf16(w[2] * gk[2][b], w[3] * gk[3][b]); o.z = cvt_pk_bf16(w[4] * gk[4][b], w[5] * gk[5][b]); o.w = cvt_pk_bf16(w[6] * gk[6][b], w[7] * gk[7][b]);
;                 __builtin_nontemporal_store(o, (u32x4*)(WT + (size_t)b * cstride + (size_t)(dst_n0 + n) * K + k0 + 8 * c)); } }
;     }
;     if (st) { const int n = lane & 31, hf = lane >> 5; f32x4 a4 = {0.f, 0.f, 0.f, 0.f};
	v_mov_b32_e32 v62, v18
	s_waitcnt lgkmcnt(6)
	v_mov_b32_e32 v63, v22
	s_waitcnt lgkmcnt(5)
	v_mov_b32_e32 v64, v26
	s_waitcnt lgkmcnt(4)
	v_mov_b32_e32 v65, v34
	v_lshl_add_u64 v[60:61], v[42:43], 0, v[30:31]
	v_pk_mul_f32 v[30:31], v[44:45], v[62:63]
	v_pk_mul_f32 v[32:33], v[46:47], v[64:65]
	s_waitcnt lgkmcnt(3)
	v_mov_b32_e32 v66, v52
	s_waitcnt lgkmcnt(2)
	v_mov_b32_e32 v67, v54
	s_waitcnt lgkmcnt(1)
	v_mov_b32_e32 v68, v56
	s_waitcnt lgkmcnt(0)
	v_mov_b32_e32 v69, v58
	v_cvt_pk_bf16_f32 v30, v30, v31
	v_cvt_pk_bf16_f32 v31, v32, v33
	v_pk_mul_f32 v[32:33], v[48:49], v[66:67]
	v_pk_mul_f32 v[70:71], v[50:51], v[68:69]
	v_cvt_pk_bf16_f32 v32, v32, v33
	v_cvt_pk_bf16_f32 v33, v70, v71
	global_store_dwordx4 v[60:61], v[30:33], off nt
	v_pk_mul_f32 v[70:71], v[4:5], v[68:69]
	v_mov_b32_e32 v22, v19
	v_pk_mul_f32 v[30:31], v[8:9], v[62:63]
	v_pk_mul_f32 v[32:33], v[0:1], v[64:65]
	v_cvt_pk_bf16_f32 v30, v30, v31
	v_cvt_pk_bf16_f32 v31, v32, v33
	v_pk_mul_f32 v[32:33], v[12:13], v[66:67]
	v_pk_mul_f32 v[18:19], v[44:45], v[22:23]
	v_cvt_pk_bf16_f32 v32, v32, v33
	v_cvt_pk_bf16_f32 v33, v70, v71
	v_add_co_u32_e32 v70, vcc, s7, v60
	v_mov_b32_e32 v34, v27
	s_nop 0
	v_addc_co_u32_e32 v71, vcc, 0, v61, vcc
	global_store_dwordx4 v[70:71], v[30:33], off nt
	v_pk_mul_f32 v[70:71], v[28:29], v[68:69]
	v_mov_b32_e32 v54, v53
	v_pk_mul_f32 v[30:31], v[16:17], v[62:63]
	v_pk_mul_f32 v[32:33], v[20:21], v[64:65]
	v_cvt_pk_bf16_f32 v30, v30, v31
	v_cvt_pk_bf16_f32 v31, v32, v33
	v_pk_mul_f32 v[32:33], v[24:25], v[66:67]
	v_mov_b32_e32 v58, v57
	v_cvt_pk_bf16_f32 v32, v32, v33
	v_cvt_pk_bf16_f32 v33, v70, v71
	v_add_co_u32_e32 v70, vcc, s12, v60
	v_pk_mul_f32 v[0:1], v[0:1], v[34:35]
	s_nop 0
	v_addc_co_u32_e32 v71, vcc, 0, v61, vcc
	global_store_dwordx4 v[70:71], v[30:33], off nt
	v_add_co_u32_e32 v60, vcc, s24, v60
	s_nop 0
	v_pk_mul_f32 v[30:31], v[10:11], v[62:63]
	v_pk_mul_f32 v[32:33], v[2:3], v[64:65]
	v_cvt_pk_bf16_f32 v30, v30, v31
	v_cvt_pk_bf16_f32 v31, v32, v33
	v_pk_mul_f32 v[32:33], v[14:15], v[66:67]
	v_pk_mul_f32 v[62:63], v[6:7], v[68:69]
	v_cvt_pk_bf16_f32 v32, v32, v33
	v_cvt_pk_bf16_f32 v33, v62, v63
	v_addc_co_u32_e32 v61, vcc, 0, v61, vcc
	global_store_dwordx4 v[60:61], v[30:33], off nt
	v_pk_mul_f32 v[8:9], v[8:9], v[22:23]
	v_pk_mul_f32 v[2:3], v[2:3], v[34:35]
	v_add_u32_e32 v30, s28, v79
	v_ashrrev_i32_e32 v31, 31, v30
	v_lshlrev_b64 v[30:31], 11, v[30:31]
	v_lshl_add_u64 v[42:43], v[42:43], 0, v[30:31]
	v_cvt_pk_bf16_f32 v30, v18, v19
	v_pk_mul_f32 v[18:19], v[46:47], v[34:35]
	s_nop 0
	v_cvt_pk_bf16_f32 v31, v18, v19
	v_pk_mul_f32 v[18:19], v[48:49], v[54:55]
	s_nop 0
	v_cvt_pk_bf16_f32 v32, v18, v19
	v_pk_mul_f32 v[18:19], v[50:51], v[58:59]
	s_nop 0
	v_cvt_pk_bf16_f32 v33, v18, v19
	global_store_dwordx4 v[42:43], v[30:33], off nt
	s_nop 1
	v_cvt_pk_bf16_f32 v31, v0, v1
	v_pk_mul_f32 v[0:1], v[12:13], v[54:55]
	v_cvt_pk_bf16_f32 v30, v8, v9
	v_cvt_pk_bf16_f32 v32, v0, v1
	v_pk_mul_f32 v[0:1], v[4:5], v[58:59]
	v_pk_mul_f32 v[4:5], v[6:7], v[58:59]
	v_cvt_pk_bf16_f32 v33, v0, v1
	v_add_co_u32_e32 v0, vcc, s7, v42
	s_ashr_i32 s7, s6, 31
	s_nop 0
	v_addc_co_u32_e32 v1, vcc, 0, v43, vcc
	global_store_dwordx4 v[0:1], v[30:33], off nt
	v_pk_mul_f32 v[0:1], v[16:17], v[22:23]
	s_lshl_b64 s[6:7], s[6:7], 14
	v_cvt_pk_bf16_f32 v16, v0, v1
	v_pk_mul_f32 v[0:1], v[20:21], v[34:35]
	s_add_u32 s6, s17, s6
	v_cvt_pk_bf16_f32 v17, v0, v1
	v_pk_mul_f32 v[0:1], v[24:25], v[54:55]
	s_addc_u32 s7, s18, s7
	v_cvt_pk_bf16_f32 v18, v0, v1
	v_pk_mul_f32 v[0:1], v[28:29], v[58:59]
	s_nop 0
	v_cvt_pk_bf16_f32 v19, v0, v1
	v_add_co_u32_e32 v0, vcc, s12, v42
	s_nop 1
	v_addc_co_u32_e32 v1, vcc, 0, v43, vcc
	global_store_dwordx4 v[0:1], v[16:19], off nt
	v_pk_mul_f32 v[0:1], v[10:11], v[22:23]
	s_nop 0
	v_cvt_pk_bf16_f32 v0, v0, v1
	v_cvt_pk_bf16_f32 v1, v2, v3
	v_pk_mul_f32 v[2:3], v[14:15], v[54:55]
	s_nop 0
	v_cvt_pk_bf16_f32 v2, v2, v3
	v_cvt_pk_bf16_f32 v3, v4, v5
	v_add_co_u32_e32 v4, vcc, s24, v42
	s_nop 1
	v_addc_co_u32_e32 v5, vcc, 0, v43, vcc
	global_store_dwordx4 v[4:5], v[0:3], off nt
	s_nop 1
	v_add_u32_e32 v0, s29, v81
	v_ashrrev_i32_e32 v1, 31, v0
	v_lshl_add_u64 v[4:5], v[0:1], 4, s[6:7]
	v_mov_b32_e32 v0, 0
	v_mov_b32_e32 v1, v0
	v_mov_b32_e32 v2, v0
	v_mov_b32_e32 v3, v0

; #define LAS __attribute__((address_space(3)))
; __device__ __forceinline__ void transpose_item(const float* W, int K, int N, bf16_t* WT, int k0, int src_n0, int dst_n0, LAS float* scr, int lane, const float* st, float* sw, const float* gt, size_t cstride) {
;     { f32x4 v[8]; const int c4 = lane & 7, kr = lane >> 3;
; #pragma unroll
;         for (int i = 0; i < 8; ++i) v[i] = __builtin_nontemporal_load((const f32x4*)(W + (size_t)(k0 + 8 * i + kr) * N + src_n0 + 4 * c4));
; #pragma unroll
;         for (int i = 0; i < 8; ++i) { LAS float* d = scr + (8 * i + kr) * 33 + 4 * c4; d[0] = v[i].x; d[1] = v[i].y; d[2] = v[i].z; d[3] = v[i].w; } }
;     asm volatile("s_waitcnt lgkmcnt(0)" ::: "memory");
;     const int c = lane & 7;
;     if (!gt) {
; #pragma unroll
;         for (int j = 0; j < 4; ++j) { const int n = (lane >> 3) + 8 * j; const LAS float* s = scr + (8 * c) * 33 + n;
;             u32x4 o; o.x = cvt_pk_bf16(s[0 * 33], s[1 * 33]); o.y = cvt_pk_bf16(s[2 * 33], s[3 * 33]); o.z = cvt_pk_bf16(s[4 * 33], s[5 * 33]); o.w = cvt_pk_bf16(s[6 * 33], s[7 * 33]);
;             __builtin_nontemporal_store(o, (u32x4*)(WT + (size_t)(dst_n0 + n) * K + k0 + 8 * c)); }
;     } else {
;         f32x4 gk[8];
; #pragma unroll
;         for (int i = 0; i < 8; ++i) gk[i] = *(const f32x4*)(gt + (size_t)(k0 + 8 * c + i) * NB);
; __device__ __forceinline__ void weights_phase(const In& I, unsigned char* ws, LAS unsigned char* lds, int tid, int lane, int wave, float* SW, int which) {
;     ...
;         if (r < 2 * I_W1) { const int f = r / I_W1; r %= I_W1; const int nblk = 2 * FF / 32, kb = r / nblk, nb = r % nblk, n0 = nb * 32;
;             const int pn = n0 >> 8, bj = (n0 >> 7) & 1, i = n0 & 127, sub = 2 * f;
;             transpose_item(I.w1 + (size_t)(l * 2 + f) * DM * 2 * FF, DM, 2 * FF, (bf16_t*)(lw + LW_W1 + (size_t)f * NB * W1_BYTES), kb * 64, bj * FF + 128 * pn + i, n0, scr, lane,
;                            ST + (size_t)(l * 3 + sub) * DM * NB, SW + (size_t)(l * 3 + sub) * NB * NSW, GT + (size_t)(l * 3 + sub) * DM * NB, W1_BYTES / 2); continue; }
.LBB0_41:
	s_andn2_b64 vcc, exec, s[6:7]
	s_cbranch_vccnz .LBB0_25
	s_mul_i32 s4, s27, 0xba3
	s_lshr_b32 s5, s4, 31
	s_ashr_i32 s4, s4, 23
	s_add_i32 s4, s4, s5
	s_sext_i32_i16 s5, s4
	s_mulk_i32 s4, 0xb00
	s_sub_i32 s4, s27, s4
	s_sext_i32_i16 s6, s4
	s_mulk_i32 s6, 0xba3
	s_lshr_b32 s7, s6, 31
	s_ashr_i32 s6, s6, 19
	s_add_i32 s6, s6, s7
	s_sext_i32_i16 s7, s6
	s_mulk_i32 s6, 0xb0
	s_sub_i32 s6, s4, s6
	s_sext_i32_i16 s12, s6
	s_lshl_b32 s27, s22, 1
	s_lshl_b32 s4, s12, 5
	s_add_i32 s27, s27, s5
	v_readlane_b32 s40, v252, 8
	s_and_b32 s24, s4, 0x60
	s_lshl_b32 s25, s5, 1
	s_mul_hi_i32 s28, s27, 0x1600000
	s_mul_i32 s27, s27, 0x1600000
	v_readlane_b32 s46, v252, 14
	v_readlane_b32 s47, v252, 15
	s_add_u32 s27, s46, s27
	s_mul_i32 s5, s5, 0x2c00000
	s_addc_u32 s29, s47, s28
	s_ashr_i32 s28, s5, 31
	s_add_u32 s40, s23, s5
	s_addc_u32 s26, s26, s28
	s_lshl_b32 s28, s7, 6
	s_bitcmp0_b32 s6, 2
	s_cselect_b32 s5, 0, 0xb00
	s_lshl_b32 s6, s12, 4
	s_and_b32 s6, s6, 0xffffff80
	s_mul_i32 s22, s22, 3
	s_add_i32 s5, s5, s6
	s_add_i32 s6, s25, s22
	s_ashr_i32 s7, s6, 31
	s_or_b32 s24, s5, s24
	s_lshl_b64 s[38:39], s[6:7], 14
	s_add_u32 s22, s11, s38
	s_addc_u32 s23, s14, s39
	s_ashr_i32 s25, s24, 31
	s_lshl_b64 s[24:25], s[24:25], 2
	s_add_u32 s24, s27, s24
	v_add_u32_e32 v30, s28, v37
	s_addc_u32 s25, s29, s25
	v_lshl_add_u64 v[28:29], s[24:25], 0, v[168:169]
	s_movk_i32 s5, 0x5800
	v_add_u32_e32 v2, 8, v30
	v_add_u32_e32 v8, 16, v30
	v_add_u32_e32 v10, 24, v30
	v_add_u32_e32 v16, 32, v30
	v_add_u32_e32 v18, 40, v30
	v_mad_i64_i32 v[0:1], s[24:25], v30, s5, v[28:29]
	s_waitcnt lgkmcnt(2)
	v_mad_i64_i32 v[4:5], s[24:25], v2, s5, v[28:29]
	v_mad_i64_i32 v[8:9], s[24:25], v8, s5, v[28:29]
	v_mad_i64_i32 v[12:13], s[24:25], v10, s5, v[28:29]
	v_mad_i64_i32 v[16:17], s[24:25], v16, s5, v[28:29]
	v_mad_i64_i32 v[20:21], s[24:25], v18, s5, v[28:29]
	v_or_b32_e32 v218, s28, v36
	v_ashrrev_i32_e32 v219, 31, v218
	v_or_b32_e32 v220, 4, v218
	v_ashrrev_i32_e32 v221, 31, v220
	v_lshl_add_u64 v[218:219], v[218:219], 4, s[22:23]
	v_lshl_add_u64 v[220:221], v[220:221], 4, s[22:23]
	global_load_dwordx4 v[186:189], v[218:219], off
	global_load_dwordx4 v[190:193], v[218:219], off offset:16
	global_load_dwordx4 v[194:197], v[218:219], off offset:32
	global_load_dwordx4 v[198:201], v[218:219], off offset:48
	global_load_dwordx4 v[202:205], v[220:221], off
	global_load_dwordx4 v[206:209], v[220:221], off offset:16
	global_load_dwordx4 v[210:213], v[220:221], off offset:32
	global_load_dwordx4 v[214:217], v[220:221], off offset:48
	global_load_dwordx4 v[0:3], v[0:1], off nt
	s_waitcnt lgkmcnt(0)
	global_load_dwordx4 v[4:7], v[4:5], off nt
	s_nop 0
	global_load_dwordx4 v[8:11], v[8:9], off nt
	s_nop 0
	global_load_dwordx4 v[12:15], v[12:13], off nt
	s_nop 0
	global_load_dwordx4 v[16:19], v[16:17], off nt
	s_nop 0
	global_load_dwordx4 v[20:23], v[20:21], off nt
	v_add_u32_e32 v24, 48, v30
	v_mad_i64_i32 v[24:25], s[24:25], v24, s5, v[28:29]
	global_load_dwordx4 v[24:27], v[24:25], off nt
	v_add_u32_e32 v30, 56, v30
	v_mad_i64_i32 v[28:29], s[24:25], v30, s5, v[28:29]
	global_load_dwordx4 v[28:31], v[28:29], off nt
	v_or_b32_e32 v32, s28, v36
	v_ashrrev_i32_e32 v33, 31, v32
	v_or_b32_e32 v34, 4, v32
	v_ashrrev_i32_e32 v35, 31, v34
	v_lshl_add_u64 v[32:33], v[32:33], 4, s[22:23]
	v_lshl_add_u64 v[34:35], v[34:35], 4, s[22:23]
	s_ashr_i32 s29, s28, 31
	s_lshl_b64 s[22:23], s[28:29], 1
	s_add_u32 s22, s40, s22
	v_mov_b32_e32 v41, v169
	s_addc_u32 s23, s26, s23
	s_mov_b32 s7, 0xb00000
	s_mov_b32 s12, 0x1600000
	s_mov_b32 s5, 0
	v_readlane_b32 s41, v252, 9
	v_readlane_b32 s42, v252, 10
	v_readlane_b32 s43, v252, 11
	v_readlane_b32 s44, v252, 12
	v_readlane_b32 s45, v252, 13
	s_waitcnt vmcnt(7)
	ds_write2_b32 v84, v0, v1 offset1:1
	ds_write2_b32 v84, v2, v3 offset0:2 offset1:3
	s_waitcnt vmcnt(6)
	ds_write2_b32 v85, v4, v5 offset1:1
	ds_write2_b32 v86, v6, v7 offset1:1
	s_waitcnt vmcnt(5)
	ds_write2_b32 v87, v8, v9 offset1:1
	ds_write2_b32 v88, v10, v11 offset1:1
	s_waitcnt vmcnt(4)
	ds_write2_b32 v89, v12, v13 offset1:1
	ds_write2_b32 v90, v14, v15 offset1:1
	s_waitcnt vmcnt(3)
	ds_write2_b32 v91, v16, v17 offset1:1
	ds_write2_b32 v92, v18, v19 offset1:1
	s_waitcnt vmcnt(2)
	ds_write2_b32 v93, v20, v21 offset1:1
	ds_write2_b32 v94, v22, v23 offset1:1
	s_waitcnt vmcnt(1)
	ds_write2_b32 v95, v24, v25 offset1:1
	ds_write2_b32 v96, v26, v27 offset1:1
	s_waitcnt vmcnt(0)
	ds_write2_b32 v97, v28, v29 offset1:1
	ds_write2_b32 v98, v30, v31 offset1:1
	s_waitcnt lgkmcnt(0)
	v_mov_b32_e32 v42, v186
	v_mov_b32_e32 v43, v187
	v_mov_b32_e32 v44, v188
	v_mov_b32_e32 v45, v189
	v_mov_b32_e32 v4, v190
	v_mov_b32_e32 v5, v191
	v_mov_b32_e32 v6, v192
	v_mov_b32_e32 v7, v193
	v_mov_b32_e32 v46, v194
	v_mov_b32_e32 v47, v195
	v_mov_b32_e32 v48, v196
	v_mov_b32_e32 v49, v197
	v_mov_b32_e32 v0, v198
	v_mov_b32_e32 v1, v199
	v_mov_b32_e32 v2, v200
	v_mov_b32_e32 v3, v201
	v_mov_b32_e32 v50, v202
	v_mov_b32_e32 v51, v203
	v_mov_b32_e32 v52, v204
	v_mov_b32_e32 v53, v205
	v_mov_b32_e32 v12, v206
	v_mov_b32_e32 v13, v207
	v_mov_b32_e32 v14, v208
	v_mov_b32_e32 v15, v209
	v_mov_b32_e32 v54, v210
	v_mov_b32_e32 v55, v211
	v_mov_b32_e32 v56, v212
	v_mov_b32_e32 v57, v213
	v_mov_b32_e32 v8, v214
	v_mov_b32_e32 v9, v215
	v_mov_b32_e32 v10, v216
	v_mov_b32_e32 v11, v217
	ds_read2_b32 v[66:67], v80 offset0:33 offset1:41
	ds_read2_b32 v[68:69], v80 offset0:66 offset1:74
	ds_read2_b32 v[70:71], v80 offset0:99 offset1:107
	ds_read2_b32 v[72:73], v80 offset1:8
	ds_read2_b32 v[74:75], v80 offset0:132 offset1:140
	ds_read2_b32 v[76:77], v80 offset0:165 offset1:173
	ds_read2_b32 v[100:101], v80 offset0:198 offset1:206
	ds_read2_b32 v[102:103], v80 offset0:231 offset1:239
	v_add_u32_e32 v16, s4, v37
	v_ashrrev_i32_e32 v17, 31, v16
	v_lshlrev_b64 v[18:19], 11, v[16:17]
	v_lshl_add_u64 v[16:17], s[22:23], 0, v[40:41]
	v_lshl_add_u64 v[34:35], v[16:17], 0, v[18:19]
	v_add_co_u32_e32 v62, vcc, s7, v34
	s_waitcnt lgkmcnt(4)
; #define LAS __attribute__((address_space(3)))
; __device__ __forceinline__ void transpose_item(const float* W, int K, int N, bf16_t* WT, int k0, int src_n0, int dst_n0, LAS float* scr, int lane, const float* st, float* sw, const float* gt, size_t cstride) {
;     ...
;         for (int j = 0; j < 4; ++j) { const int n = (lane >> 3) + 8 * j; const LAS float* s = scr + (8 * c) * 33 + n;
;             float w[8];
; #pragma unroll
;             for (int i = 0; i < 8; ++i) w[i] = s[i * 33];
; #pragma unroll
;             for (int b = 0; b < NB; ++b) {
;                 u32x4 o; o.x = cvt_pk_bf16(w[0] * gk[0][b], w[1] * gk[1][b]); o.y = cvt_pk_bf16(w[2] * gk[2][b], w[3] * gk[3][b]); o.z = cvt_pk_bf16(w[4] * gk[4][b], w[5] * gk[5][b]); o.w = cvt_pk_bf16(w[6] * gk[6][b], w[7] * gk[7][b]);
;                 __builtin_nontemporal_store(o, (u32x4*)(WT + (size_t)b * cstride + (size_t)(dst_n0 + n) * K + k0 + 8 * c)); } }
	v_mov_b32_e32 v58, v72
	v_mov_b32_e32 v59, v66
	v_mov_b32_e32 v104, v68
	v_mov_b32_e32 v105, v70
	s_waitcnt lgkmcnt(3)
	v_mov_b32_e32 v106, v74
	s_waitcnt lgkmcnt(2)
	v_mov_b32_e32 v107, v76
	s_waitcnt lgkmcnt(1)
	v_mov_b32_e32 v108, v100
	s_waitcnt lgkmcnt(0)
	v_mov_b32_e32 v109, v102
	v_addc_co_u32_e32 v63, vcc, 0, v35, vcc
	v_add_co_u32_e32 v64, vcc, s12, v34
	s_mov_b32 s22, 0x2100000
	s_nop 0
	v_addc_co_u32_e32 v65, vcc, 0, v35, vcc
	v_mov_b32_e32 v66, v73
	v_mov_b32_e32 v70, v69
	v_mov_b32_e32 v76, v75
	v_mov_b32_e32 v102, v101
	s_waitcnt vmcnt(7)
	v_mov_b32_e32 v32, v42
	s_waitcnt vmcnt(6)
	v_mov_b32_e32 v33, v4
	s_waitcnt vmcnt(5)
	v_mov_b32_e32 v30, v46
	s_waitcnt vmcnt(4)
	v_mov_b32_e32 v31, v0
	s_waitcnt vmcnt(3)
	v_mov_b32_e32 v28, v50
	s_waitcnt vmcnt(2)
	v_mov_b32_e32 v29, v12
	s_waitcnt vmcnt(1)
	v_mov_b32_e32 v26, v54
	s_waitcnt vmcnt(0)
	v_mov_b32_e32 v27, v8
	v_mov_b32_e32 v4, v43
	v_mov_b32_e32 v0, v47
	v_mov_b32_e32 v12, v51
	v_mov_b32_e32 v8, v55
	v_mov_b32_e32 v24, v44
	v_mov_b32_e32 v25, v6
	v_mov_b32_e32 v22, v48
	v_mov_b32_e32 v23, v2
	v_mov_b32_e32 v20, v52
	v_mov_b32_e32 v21, v14
	v_mov_b32_e32 v18, v56
	v_mov_b32_e32 v19, v10
	v_mov_b32_e32 v6, v45
	v_mov_b32_e32 v2, v49
	v_pk_mul_f32 v[42:43], v[32:33], v[58:59]
	v_pk_mul_f32 v[44:45], v[30:31], v[104:105]
	v_pk_mul_f32 v[46:47], v[28:29], v[106:107]
	v_pk_mul_f32 v[48:49], v[26:27], v[108:109]
	v_pk_mul_f32 v[50:51], v[4:5], v[58:59]
	v_pk_mul_f32 v[54:55], v[0:1], v[104:105]
	v_pk_mul_f32 v[60:61], v[12:13], v[106:107]
	v_pk_mul_f32 v[110:111], v[8:9], v[108:109]
	v_pk_mul_f32 v[112:113], v[24:25], v[58:59]
	v_pk_mul_f32 v[114:115], v[22:23], v[104:105]
	v_pk_mul_f32 v[116:117], v[20:21], v[106:107]
	v_cvt_pk_bf16_f32 v42, v42, v43
	v_cvt_pk_bf16_f32 v43, v44, v45
	v_pk_mul_f32 v[118:119], v[18:19], v[108:109]
	v_cvt_pk_bf16_f32 v44, v46, v47
	v_cvt_pk_bf16_f32 v45, v48, v49
	v_pk_mul_f32 v[120:121], v[6:7], v[58:59]
	v_cvt_pk_bf16_f32 v46, v50, v51
	v_cvt_pk_bf16_f32 v47, v54, v55
	v_cvt_pk_bf16_f32 v48, v60, v61
	v_cvt_pk_bf16_f32 v49, v110, v111
	v_cvt_pk_bf16_f32 v58, v112, v113
	v_cvt_pk_bf16_f32 v59, v114, v115
	v_cvt_pk_bf16_f32 v60, v116, v117
	v_cvt_pk_bf16_f32 v61, v118, v119
	global_store_dwordx4 v[34:35], v[42:45], off nt
	global_store_dwordx4 v[62:63], v[46:49], off nt
	global_store_dwordx4 v[64:65], v[58:61], off nt
	v_pk_mul_f32 v[42:43], v[2:3], v[104:105]
	v_mov_b32_e32 v14, v53
	v_cvt_pk_bf16_f32 v51, v42, v43
	v_pk_mul_f32 v[42:43], v[14:15], v[106:107]
	v_mov_b32_e32 v10, v57
	v_cvt_pk_bf16_f32 v52, v42, v43
	v_pk_mul_f32 v[42:43], v[10:11], v[108:109]
	v_add_co_u32_e32 v34, vcc, s22, v34
	v_cvt_pk_bf16_f32 v50, v120, v121
	v_cvt_pk_bf16_f32 v53, v42, v43
	v_addc_co_u32_e32 v35, vcc, 0, v35, vcc
	global_store_dwordx4 v[34:35], v[50:53], off nt
	v_add_u32_e32 v34, s4, v39
	v_ashrrev_i32_e32 v35, 31, v34
	v_pk_mul_f32 v[42:43], v[32:33], v[66:67]
	v_pk_mul_f32 v[44:45], v[30:31], v[70:71]
	v_lshlrev_b64 v[34:35], 11, v[34:35]
	v_cvt_pk_bf16_f32 v42, v42, v43
	v_cvt_pk_bf16_f32 v43, v44, v45
	v_pk_mul_f32 v[44:45], v[28:29], v[76:77]
	v_pk_mul_f32 v[46:47], v[26:27], v[102:103]
	v_lshl_add_u64 v[34:35], v[16:17], 0, v[34:35]
	v_cvt_pk_bf16_f32 v44, v44, v45
	v_cvt_pk_bf16_f32 v45, v46, v47
	global_store_dwordx4 v[34:35], v[42:45], off nt
	v_pk_mul_f32 v[46:47], v[8:9], v[102:103]
	s_nop 0
	v_pk_mul_f32 v[42:43], v[4:5], v[66:67]
	v_pk_mul_f32 v[44:45], v[0:1], v[70:71]
	v_cvt_pk_bf16_f32 v42, v42, v43
	v_cvt_pk_bf16_f32 v43, v44, v45
	v_pk_mul_f32 v[44:45], v[12:13], v[76:77]
	s_nop 0
	v_cvt_pk_bf16_f32 v44, v44, v45
	v_cvt_pk_bf16_f32 v45, v46, v47
	v_add_co_u32_e32 v46, vcc, s7, v34
	s_nop 1
	v_addc_co_u32_e32 v47, vcc, 0, v35, vcc
	global_store_dwordx4 v[46:47], v[42:45], off nt
	v_pk_mul_f32 v[46:47], v[18:19], v[102:103]
	s_nop 0
	v_pk_mul_f32 v[42:43], v[24:25], v[66:67]
	v_pk_mul_f32 v[44:45], v[22:23], v[70:71]
	v_cvt_pk_bf16_f32 v42, v42, v43
	v_cvt_pk_bf16_f32 v43, v44, v45
	v_pk_mul_f32 v[44:45], v[20:21], v[76:77]
	s_nop 0
	v_cvt_pk_bf16_f32 v44, v44, v45
	v_cvt_pk_bf16_f32 v45, v46, v47
	v_add_co_u32_e32 v46, vcc, s12, v34
	s_nop 1
	v_addc_co_u32_e32 v47, vcc, 0, v35, vcc
	global_store_dwordx4 v[46:47], v[42:45], off nt
	v_pk_mul_f32 v[46:47], v[10:11], v[102:103]
	v_add_co_u32_e32 v34, vcc, s22, v34
	v_pk_mul_f32 v[42:43], v[6:7], v[66:67]
	v_pk_mul_f32 v[44:45], v[2:3], v[70:71]
	v_cvt_pk_bf16_f32 v42, v42, v43
	v_cvt_pk_bf16_f32 v43, v44, v45
	v_pk_mul_f32 v[44:45], v[14:15], v[76:77]
	v_addc_co_u32_e32 v35, vcc, 0, v35, vcc
	v_cvt_pk_bf16_f32 v44, v44, v45
	v_cvt_pk_bf16_f32 v45, v46, v47
	global_store_dwordx4 v[34:35], v[42:45], off nt
	ds_read2_b32 v[34:35], v80 offset0:16 offset1:24
	ds_read2_b32 v[46:47], v80 offset0:49 offset1:57
	ds_read2_b32 v[48:49], v80 offset0:82 offset1:90
	ds_read2_b32 v[50:51], v80 offset0:115 offset1:123
	ds_read2_b32 v[52:53], v80 offset0:148 offset1:156
	ds_read2_b32 v[54:55], v80 offset0:181 offset1:189
	ds_read2_b32 v[56:57], v80 offset0:214 offset1:222
	ds_read2_b32 v[58:59], v80 offset0:247 offset1:255
	v_add_u32_e32 v42, s4, v78
	v_ashrrev_i32_e32 v43, 31, v42
	v_lshlrev_b64 v[42:43], 11, v[42:43]
	s_waitcnt lgkmcnt(7)
; #define LAS __attribute__((address_space(3)))
; __device__ __forceinline__ void transpose_item(const float* W, int K, int N, bf16_t* WT, int k0, int src_n0, int dst_n0, LAS float* scr, int lane, const float* st, float* sw, const float* gt, size_t cstride) {
;     ...
;         for (int j = 0; j < 4; ++j) { const int n = (lane >> 3) + 8 * j; const LAS float* s = scr + (8 * c) * 33 + n;
;             float w[8];
; #pragma unroll
;             for (int i = 0; i < 8; ++i) w[i] = s[i * 33];
; #pragma unroll
;             for (int b = 0; b < NB; ++b) {
;                 u32x4 o; o.x = cvt_pk_bf16(w[0] * gk[0][b], w[1] * gk[1][b]); o.y = cvt_pk_bf16(w[2] * gk[2][b], w[3] * gk[3][b]); o.z = cvt_pk_bf16(w[4] * gk[4][b], w[5] * gk[5][b]); o.w = cvt_pk_bf16(w[6] * gk[6][b], w[7] * gk[7][b]);
;                 __builtin_nontemporal_store(o, (u32x4*)(WT + (size_t)b * cstride + (size_t)(dst_n0 + n) * K + k0 + 8 * c)); } }
;     }
;     if (st) { const int n = lane & 31, hf = lane >> 5; f32x4 a4 = {0.f, 0.f, 0.f, 0.f};
	v_mov_b32_e32 v62, v34
	s_waitcnt lgkmcnt(6)
	v_mov_b32_e32 v63, v46
	s_waitcnt lgkmcnt(5)
	v_mov_b32_e32 v64, v48
	s_waitcnt lgkmcnt(4)
	v_mov_b32_e32 v65, v50
	v_lshl_add_u64 v[60:61], v[16:17], 0, v[42:43]
	v_pk_mul_f32 v[42:43], v[32:33], v[62:63]
	v_pk_mul_f32 v[44:45], v[30:31], v[64:65]
	s_waitcnt lgkmcnt(3)
	v_mov_b32_e32 v66, v52
	s_waitcnt lgkmcnt(2)
	v_mov_b32_e32 v67, v54
	s_waitcnt lgkmcnt(1)
	v_mov_b32_e32 v68, v56
	s_waitcnt lgkmcnt(0)
	v_mov_b32_e32 v69, v58
	v_cvt_pk_bf16_f32 v42, v42, v43
	v_cvt_pk_bf16_f32 v43, v44, v45
	v_pk_mul_f32 v[44:45], v[28:29], v[66:67]
	v_pk_mul_f32 v[70:71], v[26:27], v[68:69]
	v_cvt_pk_bf16_f32 v44, v44, v45
	v_cvt_pk_bf16_f32 v45, v70, v71
	global_store_dwordx4 v[60:61], v[42:45], off nt
	v_pk_mul_f32 v[70:71], v[8:9], v[68:69]
	v_mov_b32_e32 v50, v49
	v_pk_mul_f32 v[42:43], v[4:5], v[62:63]
	v_pk_mul_f32 v[44:45], v[0:1], v[64:65]
	v_cvt_pk_bf16_f32 v42, v42, v43
	v_cvt_pk_bf16_f32 v43, v44, v45
	v_pk_mul_f32 v[44:45], v[12:13], v[66:67]
	v_mov_b32_e32 v58, v57
	v_cvt_pk_bf16_f32 v44, v44, v45
	v_cvt_pk_bf16_f32 v45, v70, v71
	v_add_co_u32_e32 v70, vcc, s7, v60
	v_mov_b32_e32 v54, v53
	s_nop 0
	v_addc_co_u32_e32 v71, vcc, 0, v61, vcc
	global_store_dwordx4 v[70:71], v[42:45], off nt
	v_pk_mul_f32 v[70:71], v[18:19], v[68:69]
	v_pk_mul_f32 v[26:27], v[26:27], v[58:59]
	v_pk_mul_f32 v[42:43], v[24:25], v[62:63]
	v_pk_mul_f32 v[44:45], v[22:23], v[64:65]
	v_cvt_pk_bf16_f32 v42, v42, v43
	v_cvt_pk_bf16_f32 v43, v44, v45
	v_pk_mul_f32 v[44:45], v[20:21], v[66:67]
	v_pk_mul_f32 v[0:1], v[0:1], v[50:51]
	v_cvt_pk_bf16_f32 v44, v44, v45
	v_cvt_pk_bf16_f32 v45, v70, v71
	v_add_co_u32_e32 v70, vcc, s12, v60
	v_mov_b32_e32 v46, v35
	s_nop 0
	v_addc_co_u32_e32 v71, vcc, 0, v61, vcc
	global_store_dwordx4 v[70:71], v[42:45], off nt
	v_add_co_u32_e32 v60, vcc, s22, v60
	s_nop 0
	v_pk_mul_f32 v[42:43], v[6:7], v[62:63]
	v_pk_mul_f32 v[44:45], v[2:3], v[64:65]
	v_cvt_pk_bf16_f32 v42, v42, v43
	v_cvt_pk_bf16_f32 v43, v44, v45
	v_pk_mul_f32 v[44:45], v[14:15], v[66:67]
	v_pk_mul_f32 v[62:63], v[10:11], v[68:69]
	v_cvt_pk_bf16_f32 v44, v44, v45
	v_cvt_pk_bf16_f32 v45, v62, v63
	v_addc_co_u32_e32 v61, vcc, 0, v61, vcc
	global_store_dwordx4 v[60:61], v[42:45], off nt
	v_pk_mul_f32 v[28:29], v[28:29], v[54:55]
	v_cvt_pk_bf16_f32 v35, v26, v27
	v_add_u32_e32 v42, s4, v79
	v_ashrrev_i32_e32 v43, 31, v42
	v_lshlrev_b64 v[42:43], 11, v[42:43]
	v_cvt_pk_bf16_f32 v27, v0, v1
	v_pk_mul_f32 v[0:1], v[12:13], v[54:55]
	v_lshl_add_u64 v[16:17], v[16:17], 0, v[42:43]
	v_cvt_pk_bf16_f32 v34, v28, v29
	v_cvt_pk_bf16_f32 v28, v0, v1
	v_pk_mul_f32 v[0:1], v[8:9], v[58:59]
	v_pk_mul_f32 v[4:5], v[4:5], v[46:47]
	v_cvt_pk_bf16_f32 v29, v0, v1
	v_add_co_u32_e32 v0, vcc, s7, v16
	v_cvt_pk_bf16_f32 v26, v4, v5
	s_nop 0
	v_addc_co_u32_e32 v1, vcc, 0, v17, vcc
	global_store_dwordx4 v[0:1], v[26:29], off nt
	v_pk_mul_f32 v[0:1], v[24:25], v[46:47]
	v_pk_mul_f32 v[2:3], v[2:3], v[50:51]
	v_cvt_pk_bf16_f32 v24, v0, v1
	v_pk_mul_f32 v[0:1], v[22:23], v[50:51]
	v_pk_mul_f32 v[4:5], v[10:11], v[58:59]
	v_cvt_pk_bf16_f32 v25, v0, v1
	v_pk_mul_f32 v[0:1], v[20:21], v[54:55]
	v_pk_mul_f32 v[32:33], v[32:33], v[46:47]
	v_cvt_pk_bf16_f32 v26, v0, v1
	v_pk_mul_f32 v[0:1], v[18:19], v[58:59]
	v_pk_mul_f32 v[30:31], v[30:31], v[50:51]
	v_cvt_pk_bf16_f32 v27, v0, v1
	v_add_co_u32_e32 v0, vcc, s12, v16
	v_cvt_pk_bf16_f32 v32, v32, v33
	s_nop 0
	v_addc_co_u32_e32 v1, vcc, 0, v17, vcc
	global_store_dwordx4 v[0:1], v[24:27], off nt
	v_pk_mul_f32 v[0:1], v[6:7], v[46:47]
	v_cvt_pk_bf16_f32 v33, v30, v31
	v_cvt_pk_bf16_f32 v0, v0, v1
	v_cvt_pk_bf16_f32 v1, v2, v3
	v_pk_mul_f32 v[2:3], v[14:15], v[54:55]
	global_store_dwordx4 v[16:17], v[32:35], off nt
	v_cvt_pk_bf16_f32 v2, v2, v3
	v_cvt_pk_bf16_f32 v3, v4, v5
	v_add_co_u32_e32 v4, vcc, s22, v16
	s_add_u32 s22, s19, s38
	s_nop 0
	v_addc_co_u32_e32 v5, vcc, 0, v17, vcc
	global_store_dwordx4 v[4:5], v[0:3], off nt
	s_addc_u32 s23, s20, s39
	s_nop 0
	v_add_u32_e32 v0, s28, v81
	v_ashrrev_i32_e32 v1, 31, v0
	v_lshl_add_u64 v[4:5], v[0:1], 4, s[22:23]
	v_mov_b32_e32 v0, 0
	v_mov_b32_e32 v1, v0
	v_mov_b32_e32 v2, v0
	v_mov_b32_e32 v3, v0

; #define LAS __attribute__((address_space(3)))
; __device__ __forceinline__ int tpos(int t) { return (t & ~2047) | ((t & 15) << 7) | ((t & 2047) >> 4); }
; template <int T0, int NT, bool FIRST>
; __device__ __forceinline__ void attn_group(LAS const unsigned char* Kl, LAS const unsigned char* Vl, const bf16x8 (&qf)[4], f32x16 (&o)[2], float& mx, float& l, int nb, int w, int lane) {
;     const int r32 = lane & 31, hi = lane >> 5;
;     f32x16 s[NT];
; #pragma unroll
;     for (int t = 0; t < NT; ++t) { const float z = (T0 + t < 4 && nb == 0 && w + T0 + t < 4) ? NEGBIG : 0.f;
;         s[t] = (f32x16){z, z, z, z, z, z, z, z, z, z, z, z, z, z, z, z}; }
;     {
;         LAS const unsigned char* kp = Kl + (32 * (w + T0) + r32) * 128;
;         const int sw = (r32 >> 1) & 7;
; #pragma unroll
;         for (int ks = 0; ks < 4; ++ks) {
;             bf16x8 kf[NT];
; #pragma unroll
;             for (int t = 0; t < NT; ++t) kf[t] = *(LAS const bf16x8*)(kp + t * 4096 + (((2 * ks + hi) ^ sw) * 16));
; #pragma unroll
;             for (int t = 0; t < NT; ++t) s[t] = __builtin_amdgcn_mfma_f32_32x32x16_bf16(kf[t], qf[ks], s[t], 0, 0, 0);
;         }
;     }
; template <bool FINAL>
; __device__ __forceinline__ void attn_compute(LAS unsigned char* lds, const bf16_t* proj, const AttnItem& t, const AttnItem& nxt, bool more, bf16x8 (&qf)[4], bf16_t* o23, float* lse23, bf16_t* ycat, int lane, int wid) {
;     ...
;     const int tok = (nb * 128 + 32 * w + r32) * t.dil + t.r;
;     const size_t qrow = (size_t)t.b * SEQ + tok, hrow = (size_t)(t.b * NH + t.h) * SEQ + tpos(tok);
;     float l2 = 0.f, l3 = 0.f; u32x2 a2[8], a3[8];
;     if (FINAL) { l2 = lse23[hrow]; l3 = lse23[(size_t)M * NH + hrow];
;         const bf16_t* o2 = o23 + hrow * HD + 4 * hi; const bf16_t* o3 = o2 + (size_t)M * AW;
; #pragma unroll
;         for (int i = 0; i < 8; ++i) { a2[i] = *(const u32x2*)(o2 + 32 * (i >> 2) + 8 * (i & 3)); a3[i] = *(const u32x2*)(o3 + 32 * (i >> 2) + 8 * (i & 3)); } }
.LBB0_474:
	s_lshl_b32 s10, s14, 1
	s_add_i32 s10, s10, s16
	s_ashr_i32 s20, s10, 9
	s_bfe_u32 s21, s10, 0x30006
	s_lshl_b32 s14, s20, 3
	s_and_b32 s22, s10, 63
	s_or_b32 s24, s14, s21
	s_lshl_b32 s14, s22, 7
	s_and_b32 s10, s14, 0x1f00
	s_add_i32 s19, s10, 0xffffff80
	v_add_u32_e32 v0, s19, v138
	v_add_u32_e32 v1, s10, v138
	v_cmp_gt_i32_e32 vcc, 0, v0
	s_ashr_i32 s25, s24, 31
	s_lshl_b64 s[26:27], s[24:25], 21
	v_cndmask_b32_e32 v187, v0, v1, vcc
	v_add_u32_e32 v0, s19, v139
	v_add_u32_e32 v1, s10, v139
	v_cmp_gt_i32_e32 vcc, 0, v0
	v_add_u32_e32 v33, v147, v148
	v_lshl_add_u64 v[88:89], v[98:99], 0, s[26:27]
	v_cndmask_b32_e32 v87, v0, v1, vcc
	v_add_u32_e32 v0, s19, v140
	v_add_u32_e32 v1, s10, v140
	v_cmp_gt_i32_e32 vcc, 0, v0
	ds_read_b128 v[10:13], v33
	ds_read_b128 v[34:37], v33 offset:4096
	v_cndmask_b32_e32 v86, v0, v1, vcc
	v_add_u32_e32 v0, s19, v141
	v_add_u32_e32 v1, s10, v141
	v_cmp_gt_i32_e32 vcc, 0, v0
	s_ashr_i32 s99, s98, 31
	v_readlane_b32 s44, v250, 4
	v_cndmask_b32_e32 v85, v0, v1, vcc
	v_add_u32_e32 v0, s19, v142
	v_add_u32_e32 v1, s10, v142
	v_cmp_gt_i32_e32 vcc, 0, v0
	v_readlane_b32 s45, v250, 5
	v_add_u32_e32 v131, v155, v149
	v_cndmask_b32_e32 v84, v0, v1, vcc
	v_add_u32_e32 v1, s10, v143
	s_lshl_b32 s10, s98, 3
	s_or_b32 s26, s10, s12
	v_add_u32_e32 v0, s19, v143
	s_ashr_i32 s27, s26, 31
	s_lshl_b32 s19, s23, 7
	s_lshl_b64 s[26:27], s[26:27], 13
	s_and_b32 s10, s19, 0x1800
	v_cmp_gt_i32_e32 vcc, 0, v0
	s_cmp_eq_u32 s23, 0
	v_or_b32_e32 v188, s19, v146
	v_cndmask_b32_e32 v186, v0, v1, vcc
	s_cselect_b64 vcc, -1, 0
	v_bfe_u32 v1, v188, 4, 7
	v_cndmask_b32_e32 v32, 0, v227, vcc
	s_and_b64 vcc, vcc, s[44:45]
	s_or_b32 s23, s23, s18
	v_or_b32_e32 v1, s10, v1
	s_cmp_eq_u32 s23, 0
	v_or3_b32 v2, v1, v145, s26
	v_mov_b32_e32 v3, s27
	v_readlane_b32 s26, v251, 61
	v_cndmask_b32_e32 v16, 0, v227, vcc
	s_cselect_b64 vcc, -1, 0
	v_readlane_b32 s27, v251, 62
	v_or_b32_e32 v1, s14, v144
	v_cndmask_b32_e32 v0, 0, v227, vcc
	v_lshl_add_u64 v[82:83], v[2:3], 2, s[26:27]
	v_lshlrev_b64 v[2:3], 7, v[2:3]
	v_lshrrev_b32_e32 v1, 4, v1
	v_mov_b32_e32 v17, v16
	v_mov_b32_e32 v18, v16
	v_mov_b32_e32 v19, v16
	v_mov_b32_e32 v20, v16
	v_mov_b32_e32 v21, v16
	v_mov_b32_e32 v22, v16
	v_mov_b32_e32 v23, v16
	v_mov_b32_e32 v24, v16
	v_mov_b32_e32 v25, v16
	v_mov_b32_e32 v26, v16
	v_mov_b32_e32 v27, v16
	v_mov_b32_e32 v28, v16
	v_mov_b32_e32 v29, v16
	v_mov_b32_e32 v30, v16
	v_mov_b32_e32 v31, v16
	v_lshl_add_u64 v[106:107], v[100:101], 0, v[2:3]
	v_or_b32_e32 v90, s14, v1
	v_mov_b32_e32 v1, v0
	v_mov_b32_e32 v2, v0
	v_mov_b32_e32 v3, v0
	v_mov_b32_e32 v4, v0
	v_mov_b32_e32 v5, v0
	v_mov_b32_e32 v6, v0
	v_mov_b32_e32 v7, v0
	v_mov_b32_e32 v8, v0
	s_waitcnt vmcnt(3) lgkmcnt(1)
	v_mfma_f32_32x32x16_bf16 v[16:31], v[10:13], v[76:79], v[16:31]
	v_mov_b32_e32 v9, v0
	v_mov_b32_e32 v10, v0
	v_mov_b32_e32 v11, v0
	v_mov_b32_e32 v12, v0
	v_mov_b32_e32 v13, v0
	v_mov_b32_e32 v14, v0
	v_mov_b32_e32 v15, v0
	s_mov_b32 s10, 0x100000
	v_add_co_u32_e32 v80, vcc, s10, v82
	s_waitcnt lgkmcnt(0)
	v_mfma_f32_32x32x16_bf16 v[0:15], v[34:37], v[76:79], v[0:15]
	ds_read_b128 v[34:37], v33 offset:8192
	v_add_u32_e32 v33, v147, v149
	ds_read_b128 v[50:53], v33
	v_addc_co_u32_e32 v81, vcc, 0, v83, vcc
	s_brev_b32 s10, 64
	v_add_co_u32_e32 v104, vcc, s10, v106
	s_waitcnt vmcnt(2) lgkmcnt(0)
	v_mfma_f32_32x32x16_bf16 v[16:31], v[50:53], v[72:75], v[16:31]
	ds_read_b128 v[50:53], v33 offset:4096
	v_addc_co_u32_e32 v105, vcc, 0, v107, vcc
	s_lshl_b64 s[24:25], s[24:25], 20
	v_readlane_b32 s26, v251, 59
	v_readlane_b32 s27, v251, 60
	s_add_u32 vcc_lo, s26, s24
	s_waitcnt lgkmcnt(0)
	v_mfma_f32_32x32x16_bf16 v[0:15], v[50:53], v[72:75], v[0:15]
	ds_read_b128 v[50:53], v33 offset:8192
	v_add_u32_e32 v33, v147, v150
	s_addc_u32 vcc_hi, s27, s25
	v_readlane_b32 s24, v250, 6
	v_readlane_b32 s25, v250, 7
	s_movk_i32 s10, 0x187f
	v_readlane_b32 s26, v251, 57
	v_mfma_f32_32x32x16_bf16 v[34:49], v[34:37], v[76:79], 0
	v_readlane_b32 s27, v251, 58
	s_mov_b32 s23, s22
	s_waitcnt lgkmcnt(0)
	v_mfma_f32_32x32x16_bf16 v[34:49], v[50:53], v[72:75], v[34:49]
	ds_read_b128 v[50:53], v33
	s_waitcnt vmcnt(1) lgkmcnt(0)
	v_mfma_f32_32x32x16_bf16 v[16:31], v[50:53], v[68:71], v[16:31]
	ds_read_b128 v[50:53], v33 offset:4096
	s_waitcnt lgkmcnt(0)
	v_mfma_f32_32x32x16_bf16 v[0:15], v[50:53], v[68:71], v[0:15]
	ds_read_b128 v[50:53], v33 offset:8192
	v_add_u32_e32 v33, v147, v151
	s_waitcnt lgkmcnt(0)
	v_mfma_f32_32x32x16_bf16 v[34:49], v[50:53], v[68:71], v[34:49]
	ds_read_b128 v[50:53], v33
	s_waitcnt vmcnt(0) lgkmcnt(0)
	v_mfma_f32_32x32x16_bf16 v[16:31], v[50:53], v[64:67], v[16:31]
	global_load_dwordx2 v[218:219], v[104:105], off
	global_load_dwordx2 v[220:221], v[106:107], off
	global_load_dwordx2 v[230:231], v[106:107], off offset:16
	global_load_dwordx2 v[232:233], v[104:105], off offset:16
	global_load_dwordx2 v[234:235], v[106:107], off offset:32
	global_load_dwordx2 v[236:237], v[104:105], off offset:32
	global_load_dwordx2 v[238:239], v[106:107], off offset:48
	global_load_dwordx2 v[240:241], v[104:105], off offset:48
	global_load_dwordx2 v[242:243], v[106:107], off offset:64
	global_load_dwordx2 v[244:245], v[104:105], off offset:64
	global_load_dwordx2 v[246:247], v[106:107], off offset:80
	global_load_dwordx2 v[248:249], v[104:105], off offset:80
	global_load_dwordx2 v[254:255], v[106:107], off offset:96
	ds_read_b128 v[50:53], v33 offset:4096
	s_waitcnt lgkmcnt(0)
	v_mfma_f32_32x32x16_bf16 v[0:15], v[50:53], v[64:67], v[0:15]
	ds_read_b128 v[50:53], v33 offset:8192
	s_waitcnt lgkmcnt(0)
; #define LAS __attribute__((address_space(3)))
; template <int T0, int NT, bool FIRST>
; __device__ __forceinline__ void attn_group(LAS const unsigned char* Kl, LAS const unsigned char* Vl, const bf16x8 (&qf)[4], f32x16 (&o)[2], float& mx, float& l, int nb, int w, int lane) {
;     ...
;     for (int t = 0; t < NT; ++t) { const float z = (T0 + t < 4 && nb == 0 && w + T0 + t < 4) ? NEGBIG : 0.f;
;         s[t] = (f32x16){z, z, z, z, z, z, z, z, z, z, z, z, z, z, z, z}; }
;     {
;         LAS const unsigned char* kp = Kl + (32 * (w + T0) + r32) * 128;
;         const int sw = (r32 >> 1) & 7;
; #pragma unroll
;         for (int ks = 0; ks < 4; ++ks) {
;             bf16x8 kf[NT];
; #pragma unroll
;             for (int t = 0; t < NT; ++t) kf[t] = *(LAS const bf16x8*)(kp + t * 4096 + (((2 * ks + hi) ^ sw) * 16));
; #pragma unroll
;             for (int t = 0; t < NT; ++t) s[t] = __builtin_amdgcn_mfma_f32_32x32x16_bf16(kf[t], qf[ks], s[t], 0, 0, 0);
;         }
;     }
; #pragma unroll
;     for (int t = 0; t < NT; ++t) {
;         const int tt = T0 + t;
;         if (tt == 0) {
; #pragma unroll
;             for (int i = 0; i < 16; ++i) if (crow(i, hi) < r32) s[t][i] = NEGBIG; }
;         if (tt == 4) {
; #pragma unroll
;             for (int i = 0; i < 16; ++i) if (crow(i, hi) > r32) s[t][i] = NEGBIG; }
;     }
;     float m0 = s[0][0], m1 = s[0][1], m2 = s[0][2], m3 = s[0][3];
; #pragma unroll
;     for (int t = 0; t < NT; ++t)
; #pragma unroll
;         for (int i = 0; i < 16; i += 4) { m0 = fmaxf(m0, s[t][i]); m1 = fmaxf(m1, s[t][i + 1]); m2 = fmaxf(m2, s[t][i + 2]); m3 = fmaxf(m3, s[t][i + 3]); }
;     float gm = fmaxf(fmaxf(m0, m1), fmaxf(m2, m3));
;     gm = fmaxf(gm, __shfl_xor(gm, 32));
;     if (FIRST) mx = gm;
;     else { const float mn = fmaxf(mx, gm); const float f = __builtin_amdgcn_exp2f(mx - mn); l *= f; mx = mn;
; #pragma unroll
;         for (int d = 0; d < 2; ++d)
; #pragma unroll
;             for (int i = 0; i < 16; ++i) o[d][i] *= f; }
;     float l0 = 0.f, l1 = 0.f, l2 = 0.f, l3 = 0.f;
; #pragma unroll
;     for (int t = 0; t < NT; ++t)
; #pragma unroll
;         for (int i = 0; i < 16; i += 4) {
;             const float p0 = __builtin_amdgcn_exp2f(s[t][i] - mx), p1 = __builtin_amdgcn_exp2f(s[t][i + 1] - mx), p2 = __builtin_amdgcn_exp2f(s[t][i + 2] - mx), p3 = __builtin_amdgcn_exp2f(s[t][i + 3] - mx);
	v_mfma_f32_32x32x16_bf16 v[34:49], v[50:53], v[64:67], v[34:49]
	s_nop 11
	v_cndmask_b32_e64 v33, v34, v227, s[24:25]
	v_cndmask_b32_e64 v91, v33, v34, s[4:5]
	v_readlane_b32 s24, v250, 8
	v_max_f32_e32 v33, v20, v20
	v_max_f32_e32 v34, v16, v16
	v_readlane_b32 s25, v250, 9
	v_max_f32_e32 v33, v34, v33
	v_max3_f32 v33, v33, v24, v28
	v_cndmask_b32_e64 v113, v36, v227, s[24:25]
	v_readlane_b32 s24, v250, 10
	v_readlane_b32 s25, v250, 11
	v_max3_f32 v33, v33, v0, v4
	v_cndmask_b32_e64 v112, v227, v35, s[4:5]
	v_cndmask_b32_e64 v114, v37, v227, s[24:25]
	v_readlane_b32 s24, v250, 12
	v_max_f32_e32 v34, v21, v21
	v_max_f32_e32 v35, v17, v17
	v_max3_f32 v122, v33, v8, v12
	v_add_u32_e32 v33, v155, v148
	v_readlane_b32 s25, v250, 13
	v_max_f32_e32 v34, v35, v34
	v_max_f32_e32 v35, v23, v23
	v_max_f32_e32 v36, v19, v19
	ds_read_b128 v[50:53], v33
	ds_read_b128 v[92:95], v33 offset:4096
	v_cndmask_b32_e64 v115, v38, v227, s[24:25]
	v_readlane_b32 s24, v250, 14
	v_max_f32_e32 v35, v36, v35
	v_max3_f32 v36, v18, v22, v26
	v_max3_f32 v34, v34, v25, v29
	v_readlane_b32 s25, v250, 15
	v_max3_f32 v35, v35, v27, v31
	v_max3_f32 v36, v36, v30, v2
	v_max3_f32 v34, v34, v1, v5
	v_cndmask_b32_e64 v117, v39, v227, s[24:25]
	v_cndmask_b32_e64 v118, v40, v227, s[46:47]
	v_cndmask_b32_e64 v119, v41, v227, s[48:49]
	v_cndmask_b32_e64 v121, v42, v227, s[50:51]
	v_cndmask_b32_e64 v123, v43, v227, s[52:53]
	v_cndmask_b32_e64 v124, v44, v227, s[54:55]
	v_cndmask_b32_e64 v125, v45, v227, s[56:57]
	v_cndmask_b32_e64 v126, v46, v227, s[58:59]
	v_cndmask_b32_e64 v127, v47, v227, s[60:61]
	v_cndmask_b32_e64 v128, v48, v227, s[62:63]
	v_max3_f32 v116, v35, v3, v7
	v_max3_f32 v120, v36, v6, v10
	v_max3_f32 v130, v34, v9, v13
	v_cndmask_b32_e64 v48, 0, v32, s[66:67]
	v_mov_b32_e32 v33, v32
	v_mov_b32_e32 v34, v32
	v_mov_b32_e32 v35, v32
	v_mov_b32_e32 v36, v32
	v_mov_b32_e32 v37, v32
	v_mov_b32_e32 v38, v32
	v_mov_b32_e32 v39, v32
	v_mov_b32_e32 v40, v32
	v_mov_b32_e32 v41, v32
	v_mov_b32_e32 v42, v32
	v_mov_b32_e32 v43, v32
	v_mov_b32_e32 v44, v32
	v_mov_b32_e32 v45, v32
	v_mov_b32_e32 v46, v32
	v_mov_b32_e32 v47, v32
	v_cndmask_b32_e64 v129, v49, v227, s[64:65]
	v_mov_b32_e32 v49, v48
	s_waitcnt lgkmcnt(1)
	v_mfma_f32_32x32x16_bf16 v[32:47], v[50:53], v[76:79], v[32:47]
	v_mov_b32_e32 v50, v48
	v_mov_b32_e32 v51, v48
	v_mov_b32_e32 v52, v48
	v_mov_b32_e32 v53, v48
	v_mov_b32_e32 v54, v48
	v_mov_b32_e32 v55, v48
	v_mov_b32_e32 v56, v48
	v_mov_b32_e32 v57, v48
	v_mov_b32_e32 v58, v48
	v_mov_b32_e32 v59, v48
	v_mov_b32_e32 v60, v48
	v_mov_b32_e32 v61, v48
	v_mov_b32_e32 v62, v48
	v_mov_b32_e32 v63, v48
	ds_read_b128 v[108:111], v131
	global_load_dword v80, v[80:81], off
	s_waitcnt lgkmcnt(1)
	v_mfma_f32_32x32x16_bf16 v[48:63], v[92:95], v[76:79], v[48:63]
	v_max3_f32 v76, v116, v11, v15
	v_max3_f32 v77, v120, v14, v113
	v_max3_f32 v94, v76, v114, v119
	v_max3_f32 v95, v77, v118, v124
	ds_read_b128 v[76:79], v131 offset:4096
	v_max3_f32 v92, v122, v91, v115
	v_max3_f32 v93, v130, v112, v117
	v_max3_f32 v94, v94, v125, v129
	s_waitcnt lgkmcnt(1)
	v_mfma_f32_32x32x16_bf16 v[32:47], v[108:111], v[72:75], v[32:47]
	v_max3_f32 v92, v92, v121, v126
	v_max3_f32 v93, v93, v123, v127
	v_max3_f32 v94, v95, v128, v94
	v_add_u32_e32 v109, v155, v150
	v_max3_f32 v108, v92, v93, v94
	ds_read_b128 v[92:95], v109
	s_waitcnt lgkmcnt(1)
	v_mfma_f32_32x32x16_bf16 v[48:63], v[76:79], v[72:75], v[48:63]
	ds_bpermute_b32 v72, v157, v108
	s_waitcnt lgkmcnt(0)
	v_max_f32_e32 v76, v72, v72
	ds_read_b128 v[72:75], v109 offset:4096
	v_mfma_f32_32x32x16_bf16 v[32:47], v[92:95], v[68:71], v[32:47]
	v_max_f32_e32 v109, v108, v76
	v_add_u32_e32 v92, v155, v151
	v_sub_f32_e32 v19, v19, v109
	ds_read_b128 v[76:79], v92
	v_exp_f32_e32 v19, v19
	v_sub_f32_e32 v23, v23, v109
	v_exp_f32_e32 v23, v23
	s_waitcnt lgkmcnt(1)
	v_mfma_f32_32x32x16_bf16 v[48:63], v[72:75], v[68:71], v[48:63]
	v_add_f32_e32 v68, 0, v19
	v_sub_f32_e32 v27, v27, v109
	v_add_f32_e32 v72, v23, v68
	ds_read_b128 v[68:71], v92 offset:4096
	v_exp_f32_e32 v192, v27
	v_sub_f32_e32 v27, v31, v109
	v_exp_f32_e32 v193, v27
	s_waitcnt lgkmcnt(1)
	v_mfma_f32_32x32x16_bf16 v[32:47], v[76:79], v[64:67], v[32:47]
	v_sub_f32_e32 v3, v3, v109
	v_exp_f32_e32 v194, v3
	v_sub_f32_e32 v3, v7, v109
	v_sub_f32_e32 v20, v20, v109
	v_sub_f32_e32 v24, v24, v109
	v_exp_f32_e32 v20, v20
	v_exp_f32_e32 v81, v24
	s_waitcnt lgkmcnt(0)
	v_mfma_f32_32x32x16_bf16 v[48:63], v[68:71], v[64:67], v[48:63]
	s_nop 2
	v_cndmask_b32_e64 v27, v32, v227, s[4:5]
	v_cndmask_b32_e64 v36, v36, v227, s[90:91]
	v_cndmask_b32_e64 v31, v33, v227, s[96:97]
	v_cndmask_b32_e64 v37, v37, v227, s[88:89]
	v_max_f32_e32 v32, v36, v36
	v_max_f32_e32 v33, v27, v27
	v_cndmask_b32_e64 v35, v35, v227, s[92:93]
	v_cndmask_b32_e64 v39, v39, v227, s[6:7]
	v_max_f32_e32 v32, v33, v32
	v_max_f32_e32 v33, v37, v37
	v_max_f32_e32 v64, v31, v31
	v_max_f32_e32 v33, v64, v33
	v_max_f32_e32 v64, v39, v39
	v_max_f32_e32 v65, v35, v35
	v_cndmask_b32_e64 v34, v34, v227, s[94:95]
	v_cndmask_b32_e64 v38, v38, v227, s[42:43]
	v_cndmask_b32_e64 v42, v42, v227, s[0:1]
	v_cndmask_b32_e64 v43, v43, v227, s[2:3]
	v_cndmask_b32_e64 v47, v47, v227, s[68:69]
	v_max_f32_e32 v64, v65, v64
	v_cndmask_b32_e64 v40, v40, v227, s[40:41]
	v_cndmask_b32_e64 v41, v41, v227, s[38:39]
	v_cndmask_b32_e64 v44, v44, v227, s[28:29]
	v_cndmask_b32_e64 v45, v45, v227, s[76:77]
	v_cndmask_b32_e64 v46, v46, v227, s[70:71]
	v_max3_f32 v65, v34, v38, v42
	v_max3_f32 v64, v64, v43, v47
	v_max3_f32 v32, v32, v40, v44
	v_max3_f32 v33, v33, v41, v45
	v_max3_f32 v65, v65, v46, v50
	v_max3_f32 v64, v64, v51, v55
	v_max3_f32 v32, v32, v48, v52
	v_max3_f32 v33, v33, v49, v53
	v_max3_f32 v65, v65, v54, v58
	v_max3_f32 v64, v64, v59, v63
	v_max3_f32 v32, v32, v56, v60
	v_max3_f32 v33, v33, v57, v61
	v_max3_f32 v64, v65, v62, v64
	v_max3_f32 v32, v32, v33, v64
	ds_bpermute_b32 v33, v157, v32
	v_exp_f32_e32 v66, v3
	v_sub_f32_e32 v24, v25, v109
	v_sub_f32_e32 v0, v0, v109
	v_exp_f32_e32 v198, v0
	s_waitcnt lgkmcnt(0)
; template <int T0, int NT, bool FIRST>
; __device__ __forceinline__ void attn_group(LAS const unsigned char* Kl, LAS const unsigned char* Vl, const bf16x8 (&qf)[4], f32x16 (&o)[2], float& mx, float& l, int nb, int w, int lane) {
;     ...
;     float m0 = s[0][0], m1 = s[0][1], m2 = s[0][2], m3 = s[0][3];
; #pragma unroll
;     for (int t = 0; t < NT; ++t)
; #pragma unroll
;         for (int i = 0; i < 16; i += 4) { m0 = fmaxf(m0, s[t][i]); m1 = fmaxf(m1, s[t][i + 1]); m2 = fmaxf(m2, s[t][i + 2]); m3 = fmaxf(m3, s[t][i + 3]); }
;     float gm = fmaxf(fmaxf(m0, m1), fmaxf(m2, m3));
;     gm = fmaxf(gm, __shfl_xor(gm, 32));
;     if (FIRST) mx = gm;
;     else { const float mn = fmaxf(mx, gm); const float f = __builtin_amdgcn_exp2f(mx - mn); l *= f; mx = mn;
; #pragma unroll
;         for (int d = 0; d < 2; ++d)
; #pragma unroll
;             for (int i = 0; i < 16; ++i) o[d][i] *= f; }
;     float l0 = 0.f, l1 = 0.f, l2 = 0.f, l3 = 0.f;
; #pragma unroll
;     for (int t = 0; t < NT; ++t)
; #pragma unroll
;         for (int i = 0; i < 16; i += 4) {
;             const float p0 = __builtin_amdgcn_exp2f(s[t][i] - mx), p1 = __builtin_amdgcn_exp2f(s[t][i + 1] - mx), p2 = __builtin_amdgcn_exp2f(s[t][i + 2] - mx), p3 = __builtin_amdgcn_exp2f(s[t][i + 3] - mx);
;             s[t][i] = p0; s[t][i + 1] = p1; s[t][i + 2] = p2; s[t][i + 3] = p3; l0 += p0; l1 += p1; l2 += p2; l3 += p3; }
;     l += (l0 + l1) + (l2 + l3);
	v_max3_f32 v7, v109, v32, v33
	v_sub_f32_e32 v3, v27, v7
	v_exp_f32_e32 v67, v3
	v_add_f32_e32 v3, v192, v72
	v_add_f32_e32 v3, v193, v3
	v_add_f32_e32 v168, v194, v3
	v_and_or_b32 v3, v90, s10, v145
	v_pk_add_f32 v[32:33], v[66:67], v[168:169]
	v_lshlrev_b32_e32 v168, 7, v3
	v_sub_f32_e32 v3, v16, v109
	v_exp_f32_e32 v16, v3
	global_load_dword v27, v[82:83], off
	v_sub_f32_e32 v3, v17, v109
	v_exp_f32_e32 v82, v24
	v_sub_f32_e32 v24, v26, v109
	v_sub_f32_e32 v26, v28, v109
	v_exp_f32_e32 v17, v3
	v_sub_f32_e32 v3, v18, v109
	v_exp_f32_e32 v195, v26
	v_exp_f32_e32 v18, v3
	v_add_f32_e32 v3, 0, v16
	v_add_f32_e32 v3, v20, v3
	v_add_f32_e32 v3, v81, v3
	v_sub_f32_e32 v0, v1, v109
	v_add_f32_e32 v3, v195, v3
	v_exp_f32_e32 v199, v0
	v_sub_f32_e32 v0, v2, v109
	v_exp_f32_e32 v200, v0
	v_add_f32_e32 v0, v198, v3
	v_sub_f32_e32 v3, v5, v109
	v_exp_f32_e32 v201, v3
	v_sub_f32_e32 v3, v6, v109
	v_exp_f32_e32 v202, v3
	v_sub_f32_e32 v3, v4, v109
	v_exp_f32_e32 v116, v3
	v_sub_f32_e32 v3, v8, v109
	v_exp_f32_e32 v120, v3
	v_sub_f32_e32 v3, v9, v109
	v_exp_f32_e32 v203, v3
	v_sub_f32_e32 v3, v10, v109
	v_exp_f32_e32 v204, v3
	v_sub_f32_e32 v3, v11, v109
	v_exp_f32_e32 v122, v3
	v_sub_f32_e32 v3, v12, v109
	v_exp_f32_e32 v92, v3
	v_sub_f32_e32 v3, v13, v109
	v_exp_f32_e32 v205, v3
	v_sub_f32_e32 v3, v14, v109
	v_exp_f32_e32 v206, v3
	v_sub_f32_e32 v3, v15, v109
	v_exp_f32_e32 v94, v3
	v_sub_f32_e32 v3, v91, v109
	v_exp_f32_e32 v108, v3
	v_sub_f32_e32 v3, v112, v109
	v_exp_f32_e32 v207, v3
	v_sub_f32_e32 v3, v113, v109
	v_exp_f32_e32 v208, v3
	v_sub_f32_e32 v3, v114, v109
	v_sub_f32_e32 v22, v22, v109
	v_exp_f32_e32 v112, v3
	v_sub_f32_e32 v3, v115, v109
	v_exp_f32_e32 v22, v22
	v_sub_f32_e32 v26, v29, v109
	v_exp_f32_e32 v76, v3
	v_sub_f32_e32 v3, v117, v109
	v_exp_f32_e32 v83, v24
	v_exp_f32_e32 v196, v26
	v_sub_f32_e32 v26, v30, v109
	v_exp_f32_e32 v209, v3
	v_sub_f32_e32 v3, v118, v109
	v_sub_f32_e32 v21, v21, v109
	v_exp_f32_e32 v197, v26
	v_exp_f32_e32 v210, v3
	v_sub_f32_e32 v3, v119, v109
	v_add_f32_e32 v69, 0, v18
	v_exp_f32_e32 v21, v21
	v_exp_f32_e32 v78, v3
	v_sub_f32_e32 v3, v121, v109
	v_add_f32_e32 v24, v22, v69
	v_exp_f32_e32 v90, v3
	v_sub_f32_e32 v3, v123, v109
	v_add_f32_e32 v24, v83, v24
	v_exp_f32_e32 v211, v3
	v_sub_f32_e32 v3, v124, v109
	v_add_f32_e32 v68, 0, v17
	v_add_f32_e32 v1, v197, v24
	v_exp_f32_e32 v212, v3
	v_sub_f32_e32 v3, v125, v109
	v_add_f32_e32 v68, v21, v68
	v_add_f32_e32 v1, v200, v1
	v_exp_f32_e32 v110, v3
	v_sub_f32_e32 v3, v126, v109
	v_add_f32_e32 v25, v82, v68
	v_add_f32_e32 v1, v202, v1
	v_exp_f32_e32 v68, v3
	v_sub_f32_e32 v3, v127, v109
	v_add_f32_e32 v1, v204, v1
	v_exp_f32_e32 v213, v3
	v_sub_f32_e32 v3, v128, v109
	v_add_f32_e32 v1, v206, v1
	v_exp_f32_e32 v214, v3
	v_add_f32_e32 v1, v208, v1
	v_add_f32_e32 v1, v210, v1
	v_add_f32_e32 v1, v212, v1
	v_add_f32_e32 v74, v214, v1
	v_sub_f32_e32 v1, v109, v7
	v_exp_f32_e32 v136, v1
	v_sub_f32_e32 v1, v45, v7
	v_sub_f32_e32 v3, v129, v109
	v_exp_f32_e32 v109, v1
	v_sub_f32_e32 v1, v46, v7
	v_exp_f32_e32 v130, v1
	v_sub_f32_e32 v1, v47, v7
	v_exp_f32_e32 v131, v1
	v_sub_f32_e32 v1, v48, v7
	v_exp_f32_e32 v79, v1
	v_sub_f32_e32 v1, v49, v7
	v_exp_f32_e32 v77, v1
	v_sub_f32_e32 v1, v50, v7
	v_add_f32_e32 v25, v196, v25
	v_exp_f32_e32 v124, v1
	v_sub_f32_e32 v1, v51, v7
	v_add_f32_e32 v2, v199, v25
	v_exp_f32_e32 v125, v1
	v_sub_f32_e32 v1, v52, v7
	v_add_f32_e32 v2, v201, v2
	v_exp_f32_e32 v111, v1
	v_sub_f32_e32 v1, v53, v7
	v_add_f32_e32 v2, v203, v2
	v_sub_f32_e32 v4, v31, v7
	v_exp_f32_e32 v91, v1
	v_sub_f32_e32 v1, v54, v7
	v_add_f32_e32 v2, v205, v2
	v_exp_f32_e32 v117, v4
	v_sub_f32_e32 v4, v34, v7
	v_exp_f32_e32 v126, v1
	v_sub_f32_e32 v1, v55, v7
	v_add_f32_e32 v2, v207, v2
	v_exp_f32_e32 v132, v4
	v_sub_f32_e32 v4, v35, v7
	v_exp_f32_e32 v127, v1
	v_sub_f32_e32 v1, v56, v7
	v_add_f32_e32 v2, v209, v2
	v_exp_f32_e32 v133, v4
	v_sub_f32_e32 v4, v36, v7
	v_exp_f32_e32 v71, v1
	v_sub_f32_e32 v1, v57, v7
	v_add_f32_e32 v2, v211, v2
	v_exp_f32_e32 v123, v4
	v_sub_f32_e32 v4, v37, v7
	v_exp_f32_e32 v69, v1
	v_sub_f32_e32 v1, v58, v7
	v_exp_f32_e32 v121, v4
	v_sub_f32_e32 v4, v38, v7
	v_add_f32_e32 v72, v213, v2
	v_sub_f32_e32 v2, v41, v7
	v_exp_f32_e32 v114, v1
	v_sub_f32_e32 v1, v59, v7
	v_exp_f32_e32 v134, v4
	v_sub_f32_e32 v4, v39, v7
	v_exp_f32_e32 v93, v2
	v_sub_f32_e32 v2, v42, v7
	v_exp_f32_e32 v115, v1
	v_sub_f32_e32 v1, v60, v7
	v_exp_f32_e32 v135, v4
	v_exp_f32_e32 v128, v2
	v_sub_f32_e32 v2, v43, v7
	v_exp_f32_e32 v75, v1
	v_sub_f32_e32 v1, v61, v7
	v_exp_f32_e32 v70, v3
	v_sub_f32_e32 v3, v40, v7
	v_exp_f32_e32 v129, v2
	v_exp_f32_e32 v73, v1
	v_sub_f32_e32 v1, v62, v7
	v_exp_f32_e32 v95, v3
	v_sub_f32_e32 v2, v44, v7
	v_exp_f32_e32 v118, v1
	v_sub_f32_e32 v1, v63, v7
	v_exp_f32_e32 v113, v2
	v_exp_f32_e32 v119, v1
	v_pk_add_f32 v[2:3], v[132:133], 0 op_sel_hi:[1,0]
	v_mov_b32_e32 v1, v169
	v_pk_add_f32 v[2:3], v[134:135], v[2:3]
	v_pk_add_f32 v[0:1], v[116:117], v[0:1]
	v_pk_add_f32 v[2:3], v[128:129], v[2:3]
	v_pk_add_f32 v[4:5], v[122:123], v[32:33]
	v_pk_add_f32 v[0:1], v[120:121], v[0:1]
	v_pk_add_f32 v[2:3], v[130:131], v[2:3]
	v_pk_add_f32 v[4:5], v[94:95], v[4:5]
	v_pk_add_f32 v[0:1], v[92:93], v[0:1]
	v_pk_add_f32 v[2:3], v[124:125], v[2:3]
	v_pk_add_f32 v[4:5], v[112:113], v[4:5]
	v_pk_add_f32 v[0:1], v[108:109], v[0:1]
	v_pk_add_f32 v[2:3], v[126:127], v[2:3]
	v_pk_add_f32 v[4:5], v[78:79], v[4:5]
	v_pk_add_f32 v[0:1], v[76:77], v[0:1]
	v_pk_add_f32 v[2:3], v[114:115], v[2:3]
	v_pk_add_f32 v[4:5], v[110:111], v[4:5]
	v_pk_add_f32 v[0:1], v[90:91], v[0:1]
	v_pk_add_f32 v[2:3], v[118:119], v[2:3]
	v_pk_add_f32 v[4:5], v[70:71], v[4:5]
	v_pk_add_f32 v[0:1], v[68:69], v[0:1]
	v_pk_add_f32 v[2:3], v[2:3], v[2:3] op_sel_hi:[0,1]
	v_pk_add_f32 v[4:5], v[74:75], v[4:5]
	v_pk_add_f32 v[0:1], v[72:73], v[0:1]
	v_mov_b32_e32 v2, v169
	v_pk_add_f32 v[0:1], v[4:5], v[0:1]
	v_lshl_add_u64 v[64:65], vcc, 0, v[168:169]
	v_pk_add_f32 v[0:1], v[0:1], v[2:3]
	v_add_u32_e32 v72, v152, v153
	v_fmac_f32_e32 v1, v0, v136
	ds_bpermute_b32 v0, v157, v1
	v_add_u32_e32 v74, v152, v154
	v_and_b32_e32 v52, 0xfffff800, v86
	v_bfe_u32 v54, v86, 4, 7
	v_cvt_pk_bf16_f32 v60, v81, v82
	s_waitcnt lgkmcnt(0)
; #define LAS __attribute__((address_space(3)))
; template <int T0, int NT, bool FIRST>
; __device__ __forceinline__ void attn_group(LAS const unsigned char* Kl, LAS const unsigned char* Vl, const bf16x8 (&qf)[4], f32x16 (&o)[2], float& mx, float& l, int nb, int w, int lane) {
;     ...
;     const int i16 = lane & 15, q4 = i16 >> 2, p4 = i16 & 3, blk = (lane >> 4) & 1;
;     LAS const unsigned char* vb = Vl + (32 * (w + T0) + 4 * hi + q4) * 128 + 32 * blk + 8 * p4;
;     const int vsw = ((q4 >> 1) & 1) * 64;
; #pragma unroll
;     for (int t = 0; t < NT; ++t)
; #pragma unroll
;         for (int s2 = 0; s2 < 2; ++s2) {
;             u32x4 pw; pw.x = cvt_pk_bf16(s[t][8 * s2 + 0], s[t][8 * s2 + 1]); pw.y = cvt_pk_bf16(s[t][8 * s2 + 2], s[t][8 * s2 + 3]);
;             pw.z = cvt_pk_bf16(s[t][8 * s2 + 4], s[t][8 * s2 + 5]); pw.w = cvt_pk_bf16(s[t][8 * s2 + 6], s[t][8 * s2 + 7]);
;             const bf16x8 pf = __builtin_bit_cast(bf16x8, pw);
; #pragma unroll
;             for (int d = 0; d < 2; ++d) {
;                 LAS const unsigned char* vp = vb + (t * 32 + s2 * 16) * 128 + ((d * 64) ^ vsw);
;                 const s16x4 lo = vtr(vp), hi4 = vtr(vp + 8 * 128);
;                 const bf16x8 vf = (bf16x8){lo[0], lo[1], lo[2], lo[3], hi4[0], hi4[1], hi4[2], hi4[3]};
;                 o[d] = __builtin_amdgcn_mfma_f32_32x32x16_bf16(vf, pf, o[d], 0, 0, 0);
;             }
;         }
; template <bool FINAL>
; __device__ __forceinline__ void attn_compute(LAS unsigned char* lds, const bf16_t* proj, const AttnItem& t, const AttnItem& nxt, bool more, bf16x8 (&qf)[4], bf16_t* o23, float* lse23, bf16_t* ycat, int lane, int wid) {
;     ...
;     l += __shfl_xor(l, 32);
;     attn_load_q(proj, nxt, qf, lane, wid);
;     const float lse = mx + __builtin_amdgcn_logf(l);
;     if (!FINAL) {
;         const float c1 = 1.0f / l;
;         if (hi == 0) lse23[(size_t)t.br * M * NH + hrow] = lse;
;         bf16_t* ob = o23 + ((size_t)t.br * M * NH + hrow) * HD + 8 * hi;
; #pragma unroll
;         for (int d = 0; d < 2; ++d)
; #pragma unroll
;             for (int g = 0; g < 4; g += 2) { u32x2 wa, wb;
;                 wa.x = cvt_pk_bf16(o[d][4 * g] * c1, o[d][4 * g + 1] * c1); wa.y = cvt_pk_bf16(o[d][4 * g + 2] * c1, o[d][4 * g + 3] * c1);
;                 wb.x = cvt_pk_bf16(o[d][4 * g + 4] * c1, o[d][4 * g + 5] * c1); wb.y = cvt_pk_bf16(o[d][4 * g + 6] * c1, o[d][4 * g + 7] * c1);
	v_add_f32_e32 v168, v1, v0
	v_log_f32_e32 v0, v168
	v_cvt_pk_bf16_f32 v61, v83, v192
	v_cvt_pk_bf16_f32 v62, v195, v196
	v_cvt_pk_bf16_f32 v63, v197, v193
	v_add_f32_e32 v0, v7, v0
	s_waitcnt vmcnt(0)
	v_max3_f32 v1, v0, v27, v80
	v_sub_f32_e32 v0, v0, v1
	v_sub_f32_e32 v2, v27, v1
	v_exp_f32_e32 v0, v0
	v_exp_f32_e32 v189, v2
	v_sub_f32_e32 v1, v80, v1
	v_exp_f32_e32 v190, v1
	v_cvt_pk_bf16_f32 v7, v22, v23
	v_add_f32_e32 v1, v0, v189
	v_cvt_pk_bf16_f32 v196, v120, v203
	v_add_f32_e32 v1, v190, v1
	v_div_scale_f32 v2, s[24:25], v1, v1, 1.0
	v_rcp_f32_e32 v3, v2
	v_cvt_pk_bf16_f32 v197, v204, v122
	v_lshl_add_u64 v[64:65], v[96:97], 1, v[64:65]
	v_fma_f32 v4, -v2, v3, 1.0
	v_fmac_f32_e32 v3, v4, v3
	v_div_scale_f32 v4, vcc, 1.0, v1, 1.0
	v_mul_f32_e32 v5, v4, v3
	v_fma_f32 v6, -v2, v5, v4
	v_fmac_f32_e32 v5, v6, v3
	v_fma_f32 v2, -v2, v5, v4
	v_div_fmas_f32 v2, v2, v3, v5
	v_div_fixup_f32 v191, v2, v1, 1.0
	v_mul_f32_e32 v215, v0, v191
	v_div_scale_f32 v0, s[24:25], v168, v168, v215
	v_rcp_f32_e32 v1, v0
	v_cvt_pk_bf16_f32 v5, v18, v19
	v_cvt_pk_bf16_f32 v6, v20, v21
	s_lshl_b64 s[24:25], s[98:99], 24
	v_fma_f32 v2, -v0, v1, 1.0
	v_fmac_f32_e32 v1, v2, v1
	v_div_scale_f32 v2, vcc, v215, v168, v215
	v_mul_f32_e32 v3, v2, v1
	v_fma_f32 v4, -v0, v3, v2
	v_fmac_f32_e32 v3, v4, v1
	v_fma_f32 v0, -v0, v3, v2
	v_div_fmas_f32 v216, v0, v1, v3
	v_lshlrev_b32_e32 v1, 7, v187
	v_and_b32_e32 v0, 0xfffff800, v187
	v_and_b32_e32 v1, 0x780, v1
	v_bfe_u32 v2, v187, 4, 7
	v_or3_b32 v0, v1, v0, v2
	v_ashrrev_i32_e32 v1, 31, v0
	v_lshlrev_b64 v[0:1], 8, v[0:1]
	v_lshl_add_u64 v[0:1], v[88:89], 0, v[0:1]
	global_load_dwordx4 v[32:35], v[0:1], off
	global_load_dwordx4 v[36:39], v[0:1], off offset:128
	v_lshlrev_b32_e32 v1, 7, v87
	v_and_b32_e32 v0, 0xfffff800, v87
	v_and_b32_e32 v1, 0x780, v1
	v_bfe_u32 v2, v87, 4, 7
	v_or3_b32 v0, v1, v0, v2
	v_ashrrev_i32_e32 v1, 31, v0
	v_lshlrev_b64 v[0:1], 8, v[0:1]
	v_lshl_add_u64 v[12:13], v[88:89], 0, v[0:1]
	ds_read_b64_tr_b16 v[0:1], v72 offset:49152
	ds_read_b64_tr_b16 v[2:3], v72 offset:50176
	global_load_dwordx4 v[40:43], v[12:13], off
	v_cvt_pk_bf16_f32 v4, v16, v17
	ds_read_b64_tr_b16 v[8:9], v74 offset:49152
	ds_read_b64_tr_b16 v[10:11], v74 offset:50176
	s_waitcnt lgkmcnt(2)
	v_mfma_f32_32x32x16_bf16 v[16:31], v[0:3], v[4:7], 0
	global_load_dwordx4 v[44:47], v[12:13], off offset:128
	v_lshlrev_b32_e32 v0, 7, v86
	ds_read_b64_tr_b16 v[48:49], v72 offset:51200
	ds_read_b64_tr_b16 v[50:51], v72 offset:52224
	v_and_b32_e32 v53, 0x780, v0
	v_or3_b32 v52, v53, v52, v54
	ds_read_b64_tr_b16 v[56:57], v74 offset:51200
	ds_read_b64_tr_b16 v[58:59], v74 offset:52224
	v_ashrrev_i32_e32 v53, 31, v52
	s_waitcnt lgkmcnt(4)
	v_mfma_f32_32x32x16_bf16 v[0:15], v[8:11], v[4:7], 0
	v_and_b32_e32 v86, 0xfffff800, v85
	s_add_u32 s24, s26, s24
	s_addc_u32 s25, s27, s25
	s_lshl_b32 s12, s12, 7
	s_cmp_lg_u32 s15, s17
	s_mov_b32 s98, s20
	s_waitcnt lgkmcnt(2)
	v_mfma_f32_32x32x16_bf16 v[16:31], v[48:51], v[60:63], v[16:31]
	v_lshlrev_b64 v[48:49], 8, v[52:53]
	v_lshl_add_u64 v[52:53], v[88:89], 0, v[48:49]
	global_load_dwordx4 v[48:51], v[52:53], off
	s_nop 0
	global_load_dwordx4 v[52:55], v[52:53], off offset:128
	ds_read_b64_tr_b16 v[80:81], v72 offset:53248
	ds_read_b64_tr_b16 v[82:83], v72 offset:54272
	s_waitcnt lgkmcnt(2)
	v_mfma_f32_32x32x16_bf16 v[0:15], v[56:59], v[60:63], v[0:15]
	v_cvt_pk_bf16_f32 v56, v198, v199
	v_cvt_pk_bf16_f32 v57, v200, v194
	ds_read_b64_tr_b16 v[60:61], v74 offset:53248
	ds_read_b64_tr_b16 v[62:63], v74 offset:54272
	v_cvt_pk_bf16_f32 v58, v116, v201
	v_cvt_pk_bf16_f32 v59, v202, v66
	v_lshlrev_b32_e32 v66, 7, v85
	v_and_b32_e32 v66, 0x780, v66
	s_waitcnt lgkmcnt(2)
	v_mfma_f32_32x32x16_bf16 v[16:31], v[80:83], v[56:59], v[16:31]
	v_bfe_u32 v80, v85, 4, 7
	v_or3_b32 v86, v66, v86, v80
	ds_read_b64_tr_b16 v[80:81], v72 offset:55296
	ds_read_b64_tr_b16 v[82:83], v72 offset:56320
	ds_read_b64_tr_b16 v[192:193], v74 offset:55296
	ds_read_b64_tr_b16 v[194:195], v74 offset:56320
	v_cvt_pk_bf16_f32 v198, v92, v205
	v_cvt_pk_bf16_f32 v199, v206, v94
	v_ashrrev_i32_e32 v87, 31, v86
	s_waitcnt lgkmcnt(4)
	v_mfma_f32_32x32x16_bf16 v[0:15], v[60:63], v[56:59], v[0:15]
	v_lshlrev_b64 v[56:57], 8, v[86:87]
	v_lshl_add_u64 v[60:61], v[88:89], 0, v[56:57]
	global_load_dwordx4 v[56:59], v[60:61], off
	s_nop 0
	global_load_dwordx4 v[60:63], v[60:61], off offset:128
	v_lshlrev_b32_e32 v85, 7, v84
	v_and_b32_e32 v66, 0xfffff800, v84
	v_and_b32_e32 v85, 0x780, v85
	v_cvt_pk_bf16_f32 v92, v95, v93
	s_waitcnt lgkmcnt(2)
	v_mfma_f32_32x32x16_bf16 v[16:31], v[80:83], v[196:199], v[16:31]
	ds_read_b64_tr_b16 v[80:81], v72 offset:57344
	ds_read_b64_tr_b16 v[82:83], v72 offset:58368
	v_cvt_pk_bf16_f32 v93, v128, v129
	v_cvt_pk_bf16_f32 v94, v113, v109
	v_cvt_pk_bf16_f32 v95, v130, v131
	s_waitcnt lgkmcnt(2)
	v_mfma_f32_32x32x16_bf16 v[0:15], v[192:195], v[196:199], v[0:15]
	ds_read_b64_tr_b16 v[192:193], v74 offset:57344
	ds_read_b64_tr_b16 v[194:195], v74 offset:58368
	v_cvt_pk_bf16_f32 v196, v108, v207
	v_cvt_pk_bf16_f32 v197, v208, v112
	v_cvt_pk_bf16_f32 v198, v76, v209
	v_cvt_pk_bf16_f32 v199, v210, v78
	v_bfe_u32 v76, v84, 4, 7
	v_cvt_pk_bf16_f32 v78, v111, v91
	s_waitcnt lgkmcnt(2)
	v_mfma_f32_32x32x16_bf16 v[16:31], v[80:83], v[196:199], v[16:31]
	v_or3_b32 v80, v85, v66, v76
	ds_read_b64_tr_b16 v[84:85], v72 offset:59392
	ds_read_b64_tr_b16 v[86:87], v72 offset:60416
	v_ashrrev_i32_e32 v81, 31, v80
	v_lshlrev_b64 v[80:81], 8, v[80:81]
	v_lshl_add_u64 v[200:201], v[88:89], 0, v[80:81]
	global_load_dwordx4 v[80:83], v[200:201], off
	v_add_u32_e32 v72, v156, v154
	s_waitcnt lgkmcnt(2)
; #define LAS __attribute__((address_space(3)))
; __device__ __forceinline__ s16x4 vtr(LAS const unsigned char* p) { return __builtin_bit_cast(s16x4, __builtin_amdgcn_ds_read_tr16_b64_v4i16((LAS v4i16_t*)p)); }
; template <int T0, int NT, bool FIRST>
; __device__ __forceinline__ void attn_group(LAS const unsigned char* Kl, LAS const unsigned char* Vl, const bf16x8 (&qf)[4], f32x16 (&o)[2], float& mx, float& l, int nb, int w, int lane) {
;     ...
;     const int i16 = lane & 15, q4 = i16 >> 2, p4 = i16 & 3, blk = (lane >> 4) & 1;
;     LAS const unsigned char* vb = Vl + (32 * (w + T0) + 4 * hi + q4) * 128 + 32 * blk + 8 * p4;
;     const int vsw = ((q4 >> 1) & 1) * 64;
; #pragma unroll
;     for (int t = 0; t < NT; ++t)
; #pragma unroll
;         for (int s2 = 0; s2 < 2; ++s2) {
;             u32x4 pw; pw.x = cvt_pk_bf16(s[t][8 * s2 + 0], s[t][8 * s2 + 1]); pw.y = cvt_pk_bf16(s[t][8 * s2 + 2], s[t][8 * s2 + 3]);
;             pw.z = cvt_pk_bf16(s[t][8 * s2 + 4], s[t][8 * s2 + 5]); pw.w = cvt_pk_bf16(s[t][8 * s2 + 6], s[t][8 * s2 + 7]);
;             const bf16x8 pf = __builtin_bit_cast(bf16x8, pw);
; #pragma unroll
;             for (int d = 0; d < 2; ++d) {
;                 LAS const unsigned char* vp = vb + (t * 32 + s2 * 16) * 128 + ((d * 64) ^ vsw);
;                 const s16x4 lo = vtr(vp), hi4 = vtr(vp + 8 * 128);
;                 const bf16x8 vf = (bf16x8){lo[0], lo[1], lo[2], lo[3], hi4[0], hi4[1], hi4[2], hi4[3]};
;                 o[d] = __builtin_amdgcn_mfma_f32_32x32x16_bf16(vf, pf, o[d], 0, 0, 0);
;             }
;         }
; template <bool FINAL>
; __device__ __forceinline__ void attn_compute(LAS unsigned char* lds, const bf16_t* proj, const AttnItem& t, const AttnItem& nxt, bool more, bf16x8 (&qf)[4], bf16_t* o23, float* lse23, bf16_t* ycat, int lane, int wid) {
;     ...
;     if (FINAL) { l2 = lse23[hrow]; l3 = lse23[(size_t)M * NH + hrow];
;         const bf16_t* o2 = o23 + hrow * HD + 4 * hi; const bf16_t* o3 = o2 + (size_t)M * AW;
; #pragma unroll
;         for (int i = 0; i < 8; ++i) { a2[i] = *(const u32x2*)(o2 + 32 * (i >> 2) + 8 * (i & 3)); a3[i] = *(const u32x2*)(o3 + 32 * (i >> 2) + 8 * (i & 3)); } }
	v_mfma_f32_32x32x16_bf16 v[0:15], v[192:195], v[196:199], v[0:15]
	ds_read_b64_tr_b16 v[192:193], v74 offset:59392
	ds_read_b64_tr_b16 v[194:195], v74 offset:60416
	v_cvt_pk_bf16_f32 v196, v90, v211
	v_cvt_pk_bf16_f32 v197, v212, v110
	v_cvt_pk_bf16_f32 v198, v68, v213
	v_cvt_pk_bf16_f32 v199, v214, v70
	v_add_u32_e32 v70, v156, v153
	v_lshlrev_b32_e32 v68, 7, v186
	s_waitcnt lgkmcnt(2)
	v_mfma_f32_32x32x16_bf16 v[16:31], v[84:87], v[196:199], v[16:31]
	global_load_dwordx4 v[84:87], v[200:201], off offset:128
	s_nop 0
	v_mov_b32_e32 v200, v220
	v_mov_b32_e32 v201, v221
	v_mov_b32_e32 v202, v230
	v_mov_b32_e32 v203, v231
	v_mov_b32_e32 v204, v218
	v_mov_b32_e32 v205, v219
	v_and_b32_e32 v66, 0xfffff800, v186
	v_and_b32_e32 v68, 0x780, v68
	v_cvt_pk_bf16_f32 v76, v79, v77
	v_cvt_pk_bf16_f32 v77, v124, v125
	v_cvt_pk_bf16_f32 v79, v126, v127
	s_waitcnt lgkmcnt(0)
	v_mfma_f32_32x32x16_bf16 v[0:15], v[192:195], v[196:199], v[0:15]
	ds_read_b64_tr_b16 v[192:193], v70 offset:49152
	ds_read_b64_tr_b16 v[194:195], v70 offset:50176
	v_mul_f32_e64 v30, v30, v136
	v_mul_f32_e64 v31, v31, v136
	v_mul_f32_e64 v28, v28, v136
	v_mul_f32_e64 v29, v29, v136
	v_pk_mul_f32 v[26:27], v[26:27], v[136:137] op_sel_hi:[1,0]
	v_pk_mul_f32 v[24:25], v[24:25], v[136:137] op_sel_hi:[1,0]
	v_pk_mul_f32 v[22:23], v[22:23], v[136:137] op_sel_hi:[1,0]
	v_pk_mul_f32 v[20:21], v[20:21], v[136:137] op_sel_hi:[1,0]
	v_pk_mul_f32 v[18:19], v[18:19], v[136:137] op_sel_hi:[1,0]
	v_pk_mul_f32 v[16:17], v[16:17], v[136:137] op_sel_hi:[1,0]
	v_cvt_pk_bf16_f32 v196, v67, v117
	v_cvt_pk_bf16_f32 v197, v132, v133
	v_cvt_pk_bf16_f32 v198, v123, v121
	v_cvt_pk_bf16_f32 v199, v134, v135
	ds_read_b64_tr_b16 v[120:121], v72 offset:49152
	ds_read_b64_tr_b16 v[122:123], v72 offset:50176
	s_waitcnt lgkmcnt(2)
	v_mfma_f32_32x32x16_bf16 v[16:31], v[192:195], v[196:199], v[16:31]
	ds_read_b64_tr_b16 v[132:133], v70 offset:51200
	ds_read_b64_tr_b16 v[134:135], v70 offset:52224
	v_mov_b32_e32 v116, v232
	v_mov_b32_e32 v117, v233
	v_mul_f32_e64 v14, v14, v136
	v_mul_f32_e64 v15, v15, v136
	v_pk_mul_f32 v[12:13], v[12:13], v[136:137] op_sel_hi:[1,0]
	v_pk_mul_f32 v[10:11], v[10:11], v[136:137] op_sel_hi:[1,0]
	v_pk_mul_f32 v[8:9], v[8:9], v[136:137] op_sel_hi:[1,0]
	v_pk_mul_f32 v[6:7], v[6:7], v[136:137] op_sel_hi:[1,0]
	v_pk_mul_f32 v[4:5], v[4:5], v[136:137] op_sel_hi:[1,0]
	v_pk_mul_f32 v[2:3], v[2:3], v[136:137] op_sel_hi:[1,0]
	v_pk_mul_f32 v[0:1], v[0:1], v[136:137] op_sel_hi:[1,0]
	s_waitcnt lgkmcnt(0)
	v_mfma_f32_32x32x16_bf16 v[16:31], v[132:135], v[92:95], v[16:31]
	v_bfe_u32 v67, v186, 4, 7
	v_or3_b32 v66, v68, v66, v67
	v_ashrrev_i32_e32 v67, 31, v66
	v_lshlrev_b64 v[66:67], 8, v[66:67]
	v_lshl_add_u64 v[66:67], v[88:89], 0, v[66:67]
	v_cvt_pk_bf16_f32 v68, v75, v73
	v_mul_f32_e32 v112, v189, v191
	v_mfma_f32_32x32x16_bf16 v[0:15], v[120:123], v[196:199], v[0:15]
	ds_read_b64_tr_b16 v[120:121], v72 offset:51200
	ds_read_b64_tr_b16 v[122:123], v72 offset:52224
	v_mov_b32_e32 v132, v234
	v_mov_b32_e32 v133, v235
	ds_read_b64_tr_b16 v[128:129], v70 offset:53248
	ds_read_b64_tr_b16 v[130:131], v70 offset:54272
	v_mov_b32_e32 v134, v236
	v_mov_b32_e32 v135, v237
	ds_read_b64_tr_b16 v[108:109], v72 offset:53248
	ds_read_b64_tr_b16 v[110:111], v72 offset:54272
	v_and_b32_e32 v189, 0xffff0000, v200
	s_waitcnt lgkmcnt(4)
	v_mfma_f32_32x32x16_bf16 v[0:15], v[120:123], v[92:95], v[0:15]
	global_load_dwordx4 v[88:91], v[66:67], off
	global_load_dwordx4 v[92:95], v[66:67], off offset:128
	v_mov_b32_e32 v124, v238
	v_mov_b32_e32 v125, v239
	v_mov_b32_e32 v126, v240
	v_mov_b32_e32 v127, v241
	ds_read_b64_tr_b16 v[120:121], v70 offset:55296
	ds_read_b64_tr_b16 v[122:123], v70 offset:56320
	v_cvt_pk_bf16_f32 v66, v71, v69
	v_cvt_pk_bf16_f32 v67, v114, v115
	v_cvt_pk_bf16_f32 v69, v118, v119
	v_div_fixup_f32 v114, v216, v168, v215
	v_lshlrev_b32_e32 v168, 11, v188
	s_waitcnt lgkmcnt(4)
	v_mfma_f32_32x32x16_bf16 v[16:31], v[128:131], v[76:79], v[16:31]
	v_mov_b32_e32 v128, v242
	v_mov_b32_e32 v129, v243
	v_lshlrev_b32_e32 v188, 16, v200
	s_waitcnt lgkmcnt(2)
	v_mfma_f32_32x32x16_bf16 v[0:15], v[108:111], v[76:79], v[0:15]
	ds_read_b64_tr_b16 v[76:77], v72 offset:55296
	ds_read_b64_tr_b16 v[78:79], v72 offset:56320
	v_mul_f32_e32 v110, v190, v191
	v_lshl_add_u64 v[108:109], s[24:25], 0, v[168:169]
	v_lshl_add_u64 v[108:109], v[108:109], 0, s[12:13]
	v_lshl_add_u64 v[108:109], v[102:103], 1, v[108:109]
	s_mov_b32 s12, s21
	s_waitcnt lgkmcnt(2)
	v_mfma_f32_32x32x16_bf16 v[16:31], v[120:123], v[66:69], v[16:31]
	v_mov_b32_e32 v118, v246
	v_mov_b32_e32 v119, v247
	v_mov_b32_e32 v120, v254
	v_mov_b32_e32 v121, v255
	s_nop 0
	global_load_dwordx2 v[106:107], v[106:107], off offset:112
	s_nop 0
	v_mov_b32_e32 v122, v244
	v_mov_b32_e32 v123, v245
	v_mov_b32_e32 v130, v248
	v_mov_b32_e32 v131, v249
	global_load_dwordx2 v[186:187], v[104:105], off offset:96
	s_nop 0
	global_load_dwordx2 v[104:105], v[104:105], off offset:112
	s_nop 1
	v_pk_mul_f32 v[16:17], v[16:17], v[114:115] op_sel_hi:[1,0]
	s_waitcnt lgkmcnt(0)
; __device__ __forceinline__ float bf_lo(unsigned u) { return __uint_as_float(u << 16); }
; __device__ __forceinline__ float bf_hi(unsigned u) { return __uint_as_float(u & 0xffff0000u); }
; __device__ __forceinline__ int tpos(int t) { return (t & ~2047) | ((t & 15) << 7) | ((t & 2047) >> 4); }
; __device__ __forceinline__ void attn_load_q(const bf16_t* proj, const AttnItem& t, bf16x8 (&qf)[4], int lane, int wid) {
;     const int w = wid & 3, r32 = lane & 31, hi = lane >> 5;
;     const size_t qrow = (size_t)(t.b * NH + t.h) * SEQ + tpos((t.nb * 128 + 32 * w + r32) * t.dil + t.r);
; #pragma unroll
;     for (int ks = 0; ks < 4; ++ks) qf[ks] = *(const bf16x8*)(proj + qrow * HD + 16 * ks + 8 * hi);
; }
; template <bool FINAL>
; __device__ __forceinline__ void attn_compute(LAS unsigned char* lds, const bf16_t* proj, const AttnItem& t, const AttnItem& nxt, bool more, bf16x8 (&qf)[4], bf16_t* o23, float* lse23, bf16_t* ycat, int lane, int wid) {
;     ...
;         bf16_t* yo = ycat + qrow * DM + t.h * HD + 8 * hi;
; #pragma unroll
;         for (int d = 0; d < 2; ++d)
; #pragma unroll
;             for (int g = 0; g < 4; g += 2) { u32x2 wp[2];
; #pragma unroll
;                 for (int e = 0; e < 2; ++e) { const int gg = g + e; const u32x2 b2 = a2[4 * d + gg], b3 = a3[4 * d + gg];
;                     wp[e].x = cvt_pk_bf16(c1 * o[d][4 * gg] + c2 * bf_lo(b2.x) + c3 * bf_lo(b3.x), c1 * o[d][4 * gg + 1] + c2 * bf_hi(b2.x) + c3 * bf_hi(b3.x));
;                     wp[e].y = cvt_pk_bf16(c1 * o[d][4 * gg + 2] + c2 * bf_lo(b2.y) + c3 * bf_lo(b3.y), c1 * o[d][4 * gg + 3] + c2 * bf_hi(b2.y) + c3 * bf_hi(b3.y)); }
;                 *(u32x4*)(yo + 32 * d + 8 * g) = pair16(wp[0], wp[1]); }
	v_mfma_f32_32x32x16_bf16 v[0:15], v[76:79], v[66:69], v[0:15]
	global_load_dwordx4 v[76:79], v[64:65], off
	global_load_dwordx4 v[72:75], v[64:65], off offset:32
	global_load_dwordx4 v[68:71], v[64:65], off offset:64
	s_nop 0
	global_load_dwordx4 v[64:67], v[64:65], off offset:96
	v_fma_f32 v16, v112, v188, v16
	v_fma_f32 v17, v112, v189, v17
	v_lshlrev_b32_e32 v188, 16, v204
	v_and_b32_e32 v189, 0xffff0000, v204
	v_pk_fma_f32 v[16:17], v[110:111], v[188:189], v[16:17] op_sel_hi:[0,1,1]
	v_pk_mul_f32 v[18:19], v[18:19], v[114:115] op_sel_hi:[1,0]
	v_lshlrev_b32_e32 v188, 16, v201
	v_and_b32_e32 v189, 0xffff0000, v201
	v_pk_fma_f32 v[18:19], v[112:113], v[188:189], v[18:19] op_sel_hi:[0,1,1]
	v_lshlrev_b32_e32 v188, 16, v205
	v_and_b32_e32 v189, 0xffff0000, v205
	v_pk_fma_f32 v[18:19], v[110:111], v[188:189], v[18:19] op_sel_hi:[0,1,1]
	v_cvt_pk_bf16_f32 v16, v16, v17
	v_cvt_pk_bf16_f32 v17, v18, v19
	v_pk_mul_f32 v[18:19], v[20:21], v[114:115] op_sel_hi:[1,0]
	v_lshlrev_b32_e32 v20, 16, v202
	v_and_b32_e32 v21, 0xffff0000, v202
	v_pk_fma_f32 v[18:19], v[112:113], v[20:21], v[18:19] op_sel_hi:[0,1,1]
	v_lshlrev_b32_e32 v20, 16, v116
	v_and_b32_e32 v21, 0xffff0000, v116
	v_pk_fma_f32 v[18:19], v[110:111], v[20:21], v[18:19] op_sel_hi:[0,1,1]
	v_pk_mul_f32 v[20:21], v[22:23], v[114:115] op_sel_hi:[1,0]
	v_lshlrev_b32_e32 v22, 16, v203
	v_and_b32_e32 v23, 0xffff0000, v203
	v_pk_fma_f32 v[20:21], v[112:113], v[22:23], v[20:21] op_sel_hi:[0,1,1]
	v_lshlrev_b32_e32 v22, 16, v117
	v_and_b32_e32 v23, 0xffff0000, v117
	v_pk_fma_f32 v[20:21], v[110:111], v[22:23], v[20:21] op_sel_hi:[0,1,1]
	v_cvt_pk_bf16_f32 v18, v18, v19
	v_cvt_pk_bf16_f32 v19, v20, v21
	s_nop 0
	v_permlane32_swap_b32_e32 v16, v18
	v_permlane32_swap_b32_e32 v17, v19
	global_store_dwordx4 v[108:109], v[16:19], off
	v_lshlrev_b32_e32 v20, 16, v133
	v_and_b32_e32 v21, 0xffff0000, v133
	v_pk_mul_f32 v[16:17], v[24:25], v[114:115] op_sel_hi:[1,0]
	v_lshlrev_b32_e32 v18, 16, v132
	v_and_b32_e32 v19, 0xffff0000, v132
	v_pk_fma_f32 v[16:17], v[112:113], v[18:19], v[16:17] op_sel_hi:[0,1,1]
	v_lshlrev_b32_e32 v18, 16, v134
	v_and_b32_e32 v19, 0xffff0000, v134
	v_pk_fma_f32 v[16:17], v[110:111], v[18:19], v[16:17] op_sel_hi:[0,1,1]
	v_pk_mul_f32 v[18:19], v[26:27], v[114:115] op_sel_hi:[1,0]
	v_cvt_pk_bf16_f32 v16, v16, v17
	v_pk_fma_f32 v[18:19], v[112:113], v[20:21], v[18:19] op_sel_hi:[0,1,1]
	v_lshlrev_b32_e32 v20, 16, v135
	v_and_b32_e32 v21, 0xffff0000, v135
	v_pk_fma_f32 v[18:19], v[110:111], v[20:21], v[18:19] op_sel_hi:[0,1,1]
	v_cvt_pk_bf16_f32 v17, v18, v19
	v_pk_mul_f32 v[18:19], v[28:29], v[114:115] op_sel_hi:[1,0]
	v_lshlrev_b32_e32 v20, 16, v124
	v_and_b32_e32 v21, 0xffff0000, v124
	v_pk_fma_f32 v[18:19], v[112:113], v[20:21], v[18:19] op_sel_hi:[0,1,1]
	v_lshlrev_b32_e32 v20, 16, v126
	v_and_b32_e32 v21, 0xffff0000, v126
	v_pk_fma_f32 v[18:19], v[110:111], v[20:21], v[18:19] op_sel_hi:[0,1,1]
	v_pk_mul_f32 v[20:21], v[30:31], v[114:115] op_sel_hi:[1,0]
	v_lshlrev_b32_e32 v22, 16, v125
	v_and_b32_e32 v23, 0xffff0000, v125
	v_pk_fma_f32 v[20:21], v[112:113], v[22:23], v[20:21] op_sel_hi:[0,1,1]
	v_lshlrev_b32_e32 v22, 16, v127
	v_and_b32_e32 v23, 0xffff0000, v127
	v_pk_fma_f32 v[20:21], v[110:111], v[22:23], v[20:21] op_sel_hi:[0,1,1]
	v_cvt_pk_bf16_f32 v18, v18, v19
	v_cvt_pk_bf16_f32 v19, v20, v21
	s_nop 0
	v_permlane32_swap_b32_e32 v16, v18
	v_permlane32_swap_b32_e32 v17, v19
	global_store_dwordx4 v[108:109], v[16:19], off offset:32
	v_pk_mul_f32 v[0:1], v[0:1], v[114:115] op_sel_hi:[1,0]
	v_pk_mul_f32 v[2:3], v[2:3], v[114:115] op_sel_hi:[1,0]
	v_lshlrev_b32_e32 v16, 16, v128
	v_and_b32_e32 v17, 0xffff0000, v128
	v_pk_fma_f32 v[0:1], v[112:113], v[16:17], v[0:1] op_sel_hi:[0,1,1]
	v_lshlrev_b32_e32 v16, 16, v122
	v_and_b32_e32 v17, 0xffff0000, v122
	v_pk_fma_f32 v[0:1], v[110:111], v[16:17], v[0:1] op_sel_hi:[0,1,1]
	v_lshlrev_b32_e32 v16, 16, v129
	v_and_b32_e32 v17, 0xffff0000, v129
	v_pk_fma_f32 v[2:3], v[112:113], v[16:17], v[2:3] op_sel_hi:[0,1,1]
	v_lshlrev_b32_e32 v16, 16, v123
	v_and_b32_e32 v17, 0xffff0000, v123
	v_pk_fma_f32 v[2:3], v[110:111], v[16:17], v[2:3] op_sel_hi:[0,1,1]
	v_cvt_pk_bf16_f32 v0, v0, v1
	v_cvt_pk_bf16_f32 v1, v2, v3
	v_pk_mul_f32 v[2:3], v[4:5], v[114:115] op_sel_hi:[1,0]
	v_lshlrev_b32_e32 v4, 16, v118
	v_and_b32_e32 v5, 0xffff0000, v118
	v_pk_fma_f32 v[2:3], v[112:113], v[4:5], v[2:3] op_sel_hi:[0,1,1]
	v_lshlrev_b32_e32 v4, 16, v130
	v_and_b32_e32 v5, 0xffff0000, v130
	v_pk_fma_f32 v[2:3], v[110:111], v[4:5], v[2:3] op_sel_hi:[0,1,1]
	v_pk_mul_f32 v[4:5], v[6:7], v[114:115] op_sel_hi:[1,0]
	v_lshlrev_b32_e32 v6, 16, v119
	v_and_b32_e32 v7, 0xffff0000, v119
	v_pk_fma_f32 v[4:5], v[112:113], v[6:7], v[4:5] op_sel_hi:[0,1,1]
	v_lshlrev_b32_e32 v6, 16, v131
	v_and_b32_e32 v7, 0xffff0000, v131
	v_pk_fma_f32 v[4:5], v[110:111], v[6:7], v[4:5] op_sel_hi:[0,1,1]
	v_cvt_pk_bf16_f32 v2, v2, v3
	v_cvt_pk_bf16_f32 v3, v4, v5
	s_nop 0
	v_permlane32_swap_b32_e32 v0, v2
	v_permlane32_swap_b32_e32 v1, v3
	global_store_dwordx4 v[108:109], v[0:3], off offset:64
	v_lshlrev_b32_e32 v4, 16, v121
	v_and_b32_e32 v5, 0xffff0000, v121
	v_pk_mul_f32 v[0:1], v[8:9], v[114:115] op_sel_hi:[1,0]
	v_lshlrev_b32_e32 v2, 16, v120
	v_and_b32_e32 v3, 0xffff0000, v120
	v_pk_fma_f32 v[0:1], v[112:113], v[2:3], v[0:1] op_sel_hi:[0,1,1]
	s_waitcnt vmcnt(8)
	v_lshlrev_b32_e32 v2, 16, v186
	v_and_b32_e32 v3, 0xffff0000, v186
	v_pk_fma_f32 v[0:1], v[110:111], v[2:3], v[0:1] op_sel_hi:[0,1,1]
	v_pk_mul_f32 v[2:3], v[10:11], v[114:115] op_sel_hi:[1,0]
	v_cvt_pk_bf16_f32 v0, v0, v1
	v_pk_fma_f32 v[2:3], v[112:113], v[4:5], v[2:3] op_sel_hi:[0,1,1]
	v_lshlrev_b32_e32 v4, 16, v187
	v_and_b32_e32 v5, 0xffff0000, v187
	v_pk_fma_f32 v[2:3], v[110:111], v[4:5], v[2:3] op_sel_hi:[0,1,1]
	v_cvt_pk_bf16_f32 v1, v2, v3
	v_pk_mul_f32 v[2:3], v[12:13], v[114:115] op_sel_hi:[1,0]
	v_lshlrev_b32_e32 v4, 16, v106
	v_and_b32_e32 v5, 0xffff0000, v106
	v_pk_fma_f32 v[2:3], v[112:113], v[4:5], v[2:3] op_sel_hi:[0,1,1]
	s_waitcnt vmcnt(7)
	v_lshlrev_b32_e32 v4, 16, v104
	v_and_b32_e32 v5, 0xffff0000, v104
	v_pk_fma_f32 v[2:3], v[110:111], v[4:5], v[2:3] op_sel_hi:[0,1,1]
	v_pk_mul_f32 v[4:5], v[14:15], v[114:115] op_sel_hi:[1,0]
	v_lshlrev_b32_e32 v6, 16, v107
	v_and_b32_e32 v7, 0xffff0000, v107
	v_pk_fma_f32 v[4:5], v[112:113], v[6:7], v[4:5] op_sel_hi:[0,1,1]
	v_lshlrev_b32_e32 v6, 16, v105
	v_and_b32_e32 v7, 0xffff0000, v105
	v_pk_fma_f32 v[4:5], v[110:111], v[6:7], v[4:5] op_sel_hi:[0,1,1]
	v_cvt_pk_bf16_f32 v2, v2, v3
	v_cvt_pk_bf16_f32 v3, v4, v5
	s_nop 0
	v_permlane32_swap_b32_e32 v0, v2
	v_permlane32_swap_b32_e32 v1, v3
	global_store_dwordx4 v[108:109], v[0:3], off offset:96
	s_waitcnt lgkmcnt(0)
	s_barrier
; #define LAS __attribute__((address_space(3)))
; __device__ __forceinline__ void attn_stage(LAS unsigned char* lds, const u32x4 (&kv)[6], const u32x4 (&vv)[6], int tid, int wid) {
;     LAS unsigned char* Kl = lds; LAS unsigned char* Vl = lds + 49152;
; #pragma unroll
;     for (int c = 0; c < 6; ++c) { const int idx = tid + 512 * c, j = idx >> 3, ch = idx & 7;
;         *(LAS u32x4*)(Kl + j * 128 + ((ch ^ ((j >> 1) & 7)) * 16)) = kv[c];
;         *(LAS u32x4*)(Vl + j * 128 + (((ch >> 2) ^ ((j >> 1) & 1)) * 64) + (ch & 3) * 16) = vv[c]; }
; }
; template <bool FINAL>
; __device__ __forceinline__ void attn_phase(LAS unsigned char* lds, const bf16_t* proj, bf16_t* o23, float* lse23, bf16_t* ycat, int tid, int lane, int wid) {
;     ...
;         attn_stage(lds, kv, vv, tid, wid);
;         asm volatile("s_waitcnt lgkmcnt(0)\n\ts_barrier" ::: "memory");
;         const bool more = t + 1 < NS;
;         const AttnItem nxt = attn_decode<FINAL>(round_of(more ? t + 1 : t), wid);
;         attn_load(proj, nxt, kv, vv, tid);
;         attn_compute<FINAL>(lds, proj, cur, nxt, more, qf, o23, lse23, ycat, lane, wid);
;         asm volatile("s_waitcnt lgkmcnt(0)\n\ts_barrier" ::: "memory");
;         if (!more) break;
	s_cbranch_scc0 .LBB0_480
	ds_write_b128 v158, v[32:35]
	ds_write_b128 v159, v[36:39] offset:49152
	ds_write_b128 v160, v[40:43]
	ds_write_b128 v161, v[44:47] offset:49152
	ds_write_b128 v162, v[48:51]
	ds_write_b128 v163, v[52:55] offset:49152
	ds_write_b128 v164, v[56:59]
	ds_write_b128 v165, v[60:63] offset:49152
	ds_write_b128 v166, v[80:83]
	ds_write_b128 v167, v[84:87] offset:49152
	ds_write_b128 v183, v[88:91]
	ds_write_b128 v185, v[92:95] offset:49152
	s_branch .Lattn_b_ldone
